# GEMM loops: 13-15 of 16 LDS-DMA loads per K-iteration use SGPR base + 32-bit VGPR offset (no 64-bit VALU address adds in load phases)
# speedup vs baseline: 1.0031x; 1.0023x over previous
; #define PG8_STAGE(bufoff, gbase, voff) do { _Pragma("unroll") for (int _i = 0; _i < 2; ++_i) \
;         __builtin_amdgcn_global_load_lds((const unsigned*)((const char*)(gbase) + (voff)[_i]), (PG8_LAS unsigned*)(lds + (bufoff) + ldsw + _i * 8192), 16, 0, 0); } while (0)
; #define PG8_LDA(dst, b, h) do { _Pragma("unroll") for (int m = 0; m < 4; ++m) _Pragma("unroll") for (int k = 0; k < 2; ++k) dst[m][k] = *(const PG8_LAS bf16x8*)(lds + PG8_SA(b, h) + aoff + m * 2048 + k * 1024); } while (0)
; #define PG8_LDB(dst, b, h) do { _Pragma("unroll") for (int n = 0; n < 2; ++n) _Pragma("unroll") for (int k = 0; k < 2; ++k) dst[n][k] = *(const PG8_LAS bf16x8*)(lds + PG8_SB(b, h) + boff + n * 2048 + k * 1024); } while (0)
; #define PG8_MMA(ai, bj, At, Bt) do { __builtin_amdgcn_s_setprio(1); _Pragma("unroll") for (int m = 0; m < 4; ++m) _Pragma("unroll") for (int n = 0; n < 2; ++n) _Pragma("unroll") for (int k = 0; k < 2; ++k) \
;         acc[ai][bj][m][n] = __builtin_amdgcn_mfma_f32_16x16x32_bf16(Bt[n][k], At[m][k], acc[ai][bj][m][n], 0, 0, 0); __builtin_amdgcn_s_setprio(0); } while (0)
; #define PG8_WAIT_V(n) asm volatile("s_waitcnt vmcnt(" #n ")" ::: "memory")
; #define PG8_WAIT_L(n) asm volatile("s_waitcnt lgkmcnt(" #n ")" ::: "memory")
; template <class Epi, class Sched, bool ALIGN_EPI = false, bool SP2 = false>
; __device__ __forceinline__ void gemm_phase(PG8_LAS unsigned char* lds, const Gemm g, const Sched& S, const Epi& E) {
;     ...
;             const bool last = (t == nt - 2);
;             const char* a1 = cA + (size_t)(t + 1) * kstep;
;             const char* a2 = last ? nA : cA + (size_t)(t + 2) * kstep; const char* b2 = last ? nB : cB + (size_t)(t + 2) * kstep;
;             const char* a3 = a2 + kstep; const char* b3 = b2 + kstep;
;             if (last && has_next) S.a_ready(nxt);
;             if constexpr (SP2) {
;             PG8_LDB(B0, 0, 0); PG8_LDB(B1, 0, 1); PG8_SCHED; PG8_LDA(At, 0, 0); PG8_STAGE(PG8_SA(1, 1), a1 + hstep, voffA);
;             PG8_WAIT_V(8); PG8_WAIT_L(0); PG8_BAR; PG8_MMA(0, 0, At, B0); PG8_MMA(0, 1, At, B1); PG8_BAR; PG8_SCHED;
;             PG8_LDA(At, 0, 1); PG8_STAGE(PG8_SB(0, 0), b2, voffB); PG8_STAGE(PG8_SB(0, 1), b2 + hstep, voffB); PG8_STAGE(PG8_SA(0, 0), a2, voffA);
;             PG8_WAIT_V(8); PG8_WAIT_L(0); PG8_BAR; PG8_MMA(1, 0, At, B0); PG8_MMA(1, 1, At, B1); PG8_BAR; PG8_SCHED;
.LBB0_165:
	s_add_u32 s28, s26, 0xfff80080
	s_addc_u32 s29, s27, -1
	s_add_i32 s78, 0, 0x10000
	s_cmp_eq_u32 s77, 28
	s_cselect_b32 s41, s17, s29
	s_cselect_b32 s40, s25, s28
	s_cselect_b32 s29, s23, s73
	s_cselect_b32 s28, s54, s55
	s_add_i32 s80, 0, 0x14000
	v_add_u32_e32 v154, s78, v161
	v_add_u32_e32 v158, s80, v161
	ds_read_b128 v[130:133], v154
	ds_read_b128 v[146:149], v154 offset:1024
	ds_read_b128 v[150:153], v154 offset:2048
	ds_read_b128 v[154:157], v154 offset:3072
	ds_read_b128 v[180:183], v158
	ds_read_b128 v[184:187], v158 offset:1024
	ds_read_b128 v[188:191], v158 offset:2048
	ds_read_b128 v[192:195], v158 offset:3072
	s_add_i32 m0, s45, 0xc000
	ds_read_b128 v[196:199], v164
	ds_read_b128 v[200:203], v164 offset:1024
	ds_read_b128 v[218:221], v164 offset:2048
	ds_read_b128 v[222:225], v164 offset:3072
	ds_read_b128 v[226:229], v164 offset:4096
	ds_read_b128 v[230:233], v164 offset:5120
	ds_read_b128 v[234:237], v164 offset:6144
	ds_read_b128 v[238:241], v164 offset:7168
	global_load_lds_dwordx4 v142, s[26:27]
	s_add_i32 m0, s45, 0xe000
	s_nop 0
	global_load_lds_dwordx4 v144, s[26:27]
	s_waitcnt vmcnt(8)
	s_waitcnt lgkmcnt(0)
	s_barrier
	v_mfma_f32_16x16x32_bf16 v[126:129], v[130:133], v[196:199], v[126:129]
	v_mfma_f32_16x16x32_bf16 v[118:121], v[150:153], v[196:199], v[118:121]
	v_mfma_f32_16x16x32_bf16 v[110:113], v[130:133], v[218:221], v[110:113]
	v_mfma_f32_16x16x32_bf16 v[102:105], v[150:153], v[218:221], v[102:105]
	v_mfma_f32_16x16x32_bf16 v[94:97], v[130:133], v[226:229], v[94:97]
	v_mfma_f32_16x16x32_bf16 v[86:89], v[150:153], v[226:229], v[86:89]
	v_mfma_f32_16x16x32_bf16 v[78:81], v[130:133], v[234:237], v[78:81]
	v_mfma_f32_16x16x32_bf16 v[70:73], v[150:153], v[234:237], v[70:73]
	v_mfma_f32_16x16x32_bf16 v[126:129], v[146:149], v[200:203], v[126:129]
	v_mfma_f32_16x16x32_bf16 v[118:121], v[154:157], v[200:203], v[118:121]
	v_mfma_f32_16x16x32_bf16 v[110:113], v[146:149], v[222:225], v[110:113]
	v_mfma_f32_16x16x32_bf16 v[102:105], v[154:157], v[222:225], v[102:105]
	v_mfma_f32_16x16x32_bf16 v[94:97], v[146:149], v[230:233], v[94:97]
	v_mfma_f32_16x16x32_bf16 v[86:89], v[154:157], v[230:233], v[86:89]
	v_mfma_f32_16x16x32_bf16 v[78:81], v[146:149], v[238:241], v[78:81]
	v_mfma_f32_16x16x32_bf16 v[70:73], v[154:157], v[238:241], v[70:73]
	v_mfma_f32_16x16x32_bf16 v[122:125], v[180:183], v[196:199], v[122:125]
	v_mfma_f32_16x16x32_bf16 v[114:117], v[188:191], v[196:199], v[114:117]
	v_mfma_f32_16x16x32_bf16 v[106:109], v[180:183], v[218:221], v[106:109]
	v_mfma_f32_16x16x32_bf16 v[98:101], v[188:191], v[218:221], v[98:101]
	v_mfma_f32_16x16x32_bf16 v[90:93], v[180:183], v[226:229], v[90:93]
	v_mfma_f32_16x16x32_bf16 v[82:85], v[188:191], v[226:229], v[82:85]
	v_mfma_f32_16x16x32_bf16 v[74:77], v[180:183], v[234:237], v[74:77]
	v_mfma_f32_16x16x32_bf16 v[66:69], v[188:191], v[234:237], v[66:69]
	v_mfma_f32_16x16x32_bf16 v[122:125], v[184:187], v[200:203], v[122:125]
	v_mfma_f32_16x16x32_bf16 v[114:117], v[192:195], v[200:203], v[114:117]
	v_mfma_f32_16x16x32_bf16 v[106:109], v[184:187], v[222:225], v[106:109]
	v_mfma_f32_16x16x32_bf16 v[98:101], v[192:195], v[222:225], v[98:101]
	v_mfma_f32_16x16x32_bf16 v[90:93], v[184:187], v[230:233], v[90:93]
	v_mfma_f32_16x16x32_bf16 v[82:85], v[192:195], v[230:233], v[82:85]
	v_mfma_f32_16x16x32_bf16 v[74:77], v[184:187], v[238:241], v[74:77]
	v_mfma_f32_16x16x32_bf16 v[66:69], v[192:195], v[238:241], v[66:69]
	s_barrier
	s_add_i32 s78, s78, s46
	s_mov_b32 m0, s78
	ds_read_b128 v[196:199], v164 offset:16384
	ds_read_b128 v[200:203], v164 offset:17408
	ds_read_b128 v[218:221], v164 offset:18432
	ds_read_b128 v[222:225], v164 offset:19456
	ds_read_b128 v[226:229], v164 offset:20480
	ds_read_b128 v[230:233], v164 offset:21504
	ds_read_b128 v[234:237], v164 offset:22528
	ds_read_b128 v[238:241], v164 offset:23552
	global_load_lds_dwordx4 v0, s[28:29]
	s_add_i32 m0, s78, 0x2000
	s_add_u32 vcc_lo, s28, 0x80000
	v_lshl_add_u64 v[166:167], s[28:29], 0, v[134:135]
	s_addc_u32 vcc_hi, s29, 0
	s_add_i32 s78, s80, s46
	global_load_lds_dwordx4 v134, s[28:29]
	s_mov_b32 m0, s78
	v_lshl_add_u64 v[244:245], s[40:41], 0, v[136:137]
	global_load_lds_dwordx4 v0, vcc
	s_add_i32 m0, s78, 0x2000
	s_nop 0
	global_load_lds_dwordx4 v134, vcc
	v_lshl_add_u64 v[242:243], s[40:41], 0, v[138:139]
	s_mov_b32 m0, s45
	s_nop 0
	global_load_lds_dwordx4 v138, s[40:41]
	s_mov_b32 m0, s49
	s_nop 0
	global_load_lds_dwordx4 v136, s[40:41]
	s_waitcnt vmcnt(8)
	s_waitcnt lgkmcnt(0)
	s_barrier
	v_mfma_f32_16x16x32_bf16 v[62:65], v[130:133], v[196:199], v[62:65]
	v_mfma_f32_16x16x32_bf16 v[54:57], v[150:153], v[196:199], v[54:57]
	v_mfma_f32_16x16x32_bf16 v[46:49], v[130:133], v[218:221], v[46:49]
	v_mfma_f32_16x16x32_bf16 v[38:41], v[150:153], v[218:221], v[38:41]
	v_mfma_f32_16x16x32_bf16 v[30:33], v[130:133], v[226:229], v[30:33]
	v_mfma_f32_16x16x32_bf16 v[22:25], v[150:153], v[226:229], v[22:25]
	v_mfma_f32_16x16x32_bf16 v[14:17], v[130:133], v[234:237], v[14:17]
	v_mfma_f32_16x16x32_bf16 v[6:9], v[150:153], v[234:237], v[6:9]
	v_mfma_f32_16x16x32_bf16 v[62:65], v[146:149], v[200:203], v[62:65]
	v_mfma_f32_16x16x32_bf16 v[54:57], v[154:157], v[200:203], v[54:57]
	v_mfma_f32_16x16x32_bf16 v[46:49], v[146:149], v[222:225], v[46:49]
	v_mfma_f32_16x16x32_bf16 v[38:41], v[154:157], v[222:225], v[38:41]
	v_mfma_f32_16x16x32_bf16 v[30:33], v[146:149], v[230:233], v[30:33]
	v_mfma_f32_16x16x32_bf16 v[22:25], v[154:157], v[230:233], v[22:25]
	v_mfma_f32_16x16x32_bf16 v[14:17], v[146:149], v[238:241], v[14:17]
	v_mfma_f32_16x16x32_bf16 v[6:9], v[154:157], v[238:241], v[6:9]
	v_mfma_f32_16x16x32_bf16 v[58:61], v[180:183], v[196:199], v[58:61]
	v_mfma_f32_16x16x32_bf16 v[50:53], v[188:191], v[196:199], v[50:53]
	v_mfma_f32_16x16x32_bf16 v[42:45], v[180:183], v[218:221], v[42:45]
	v_mfma_f32_16x16x32_bf16 v[34:37], v[188:191], v[218:221], v[34:37]
	v_mfma_f32_16x16x32_bf16 v[26:29], v[180:183], v[226:229], v[26:29]
	v_mfma_f32_16x16x32_bf16 v[18:21], v[188:191], v[226:229], v[18:21]
	v_mfma_f32_16x16x32_bf16 v[10:13], v[180:183], v[234:237], v[10:13]
	v_mfma_f32_16x16x32_bf16 v[2:5], v[188:191], v[234:237], v[2:5]
	v_mfma_f32_16x16x32_bf16 v[58:61], v[184:187], v[200:203], v[58:61]
	v_mfma_f32_16x16x32_bf16 v[50:53], v[192:195], v[200:203], v[50:53]
	v_mfma_f32_16x16x32_bf16 v[42:45], v[184:187], v[222:225], v[42:45]
	v_mfma_f32_16x16x32_bf16 v[34:37], v[192:195], v[222:225], v[34:37]
	v_mfma_f32_16x16x32_bf16 v[26:29], v[184:187], v[230:233], v[26:29]
	v_mfma_f32_16x16x32_bf16 v[18:21], v[192:195], v[230:233], v[18:21]
	v_mfma_f32_16x16x32_bf16 v[10:13], v[184:187], v[238:241], v[10:13]
	v_mfma_f32_16x16x32_bf16 v[2:5], v[192:195], v[238:241], v[2:5]
	s_barrier
; #define PG8_STAGE(bufoff, gbase, voff) do { _Pragma("unroll") for (int _i = 0; _i < 2; ++_i) \
;         __builtin_amdgcn_global_load_lds((const unsigned*)((const char*)(gbase) + (voff)[_i]), (PG8_LAS unsigned*)(lds + (bufoff) + ldsw + _i * 8192), 16, 0, 0); } while (0)
; #define PG8_LDA(dst, b, h) do { _Pragma("unroll") for (int m = 0; m < 4; ++m) _Pragma("unroll") for (int k = 0; k < 2; ++k) dst[m][k] = *(const PG8_LAS bf16x8*)(lds + PG8_SA(b, h) + aoff + m * 2048 + k * 1024); } while (0)
; #define PG8_LDB(dst, b, h) do { _Pragma("unroll") for (int n = 0; n < 2; ++n) _Pragma("unroll") for (int k = 0; k < 2; ++k) dst[n][k] = *(const PG8_LAS bf16x8*)(lds + PG8_SB(b, h) + boff + n * 2048 + k * 1024); } while (0)
; #define PG8_MMA(ai, bj, At, Bt) do { __builtin_amdgcn_s_setprio(1); _Pragma("unroll") for (int m = 0; m < 4; ++m) _Pragma("unroll") for (int n = 0; n < 2; ++n) _Pragma("unroll") for (int k = 0; k < 2; ++k) \
;         acc[ai][bj][m][n] = __builtin_amdgcn_mfma_f32_16x16x32_bf16(Bt[n][k], At[m][k], acc[ai][bj][m][n], 0, 0, 0); __builtin_amdgcn_s_setprio(0); } while (0)
; #define PG8_WAIT_V(n) asm volatile("s_waitcnt vmcnt(" #n ")" ::: "memory")
; #define PG8_WAIT_L(n) asm volatile("s_waitcnt lgkmcnt(" #n ")" ::: "memory")
; #define PG8_BAR __builtin_amdgcn_s_barrier()
; #define PG8_SCHED __builtin_amdgcn_sched_barrier(0)
; template <class Epi, class Sched, bool ALIGN_EPI = false, bool SP2 = false>
; __device__ __forceinline__ void gemm_phase(PG8_LAS unsigned char* lds, const Gemm g, const Sched& S, const Epi& E) {
;     ...
;             PG8_LDB(B0, 1, 0); PG8_LDB(B1, 1, 1); PG8_SCHED; PG8_LDA(At, 1, 0); PG8_STAGE(PG8_SA(0, 1), a2 + hstep, voffA);
;             PG8_WAIT_V(8); PG8_WAIT_L(0); PG8_BAR; PG8_MMA(0, 0, At, B0); PG8_MMA(0, 1, At, B1); PG8_BAR; PG8_SCHED;
;             PG8_LDA(At, 1, 1); PG8_STAGE(PG8_SB(1, 0), b3, voffB); PG8_STAGE(PG8_SB(1, 1), b3 + hstep, voffB); PG8_STAGE(PG8_SA(1, 0), a3, voffA);
;             PG8_WAIT_V(8); PG8_WAIT_L(0); PG8_BAR; PG8_MMA(1, 0, At, B0); PG8_MMA(1, 1, At, B1); PG8_BAR; PG8_SCHED;
;     ...
;         if constexpr (ALIGN_EPI) { if (wr == 0) PG8_BAR; }
	s_add_i32 s78, 0, 0x18000
	s_add_i32 s80, 0, 0x1c000
	v_add_u32_e32 v154, s78, v161
	v_add_u32_e32 v165, s80, v161
	ds_read_b128 v[130:133], v154
	ds_read_b128 v[146:149], v154 offset:1024
	ds_read_b128 v[150:153], v154 offset:2048
	ds_read_b128 v[154:157], v154 offset:3072
	ds_read_b128 v[180:183], v165
	ds_read_b128 v[184:187], v165 offset:1024
	ds_read_b128 v[188:191], v165 offset:2048
	ds_read_b128 v[192:195], v165 offset:3072
	s_add_u32 s40, s40, 0x80000
	s_addc_u32 s41, s41, 0
	s_mov_b32 m0, s50
	ds_read_b128 v[196:199], v164 offset:32768
	ds_read_b128 v[200:203], v164 offset:33792
	ds_read_b128 v[218:221], v164 offset:34816
	ds_read_b128 v[222:225], v164 offset:35840
	ds_read_b128 v[226:229], v164 offset:36864
	ds_read_b128 v[230:233], v164 offset:37888
	ds_read_b128 v[234:237], v164 offset:38912
	ds_read_b128 v[238:241], v164 offset:39936
	global_load_lds_dwordx4 v138, s[40:41]
	s_mov_b32 m0, s51
	s_nop 0
	global_load_lds_dwordx4 v136, s[40:41]
	s_waitcnt vmcnt(8)
	s_waitcnt lgkmcnt(0)
	s_barrier
	v_mfma_f32_16x16x32_bf16 v[126:129], v[130:133], v[196:199], v[126:129]
	v_mfma_f32_16x16x32_bf16 v[118:121], v[150:153], v[196:199], v[118:121]
	v_mfma_f32_16x16x32_bf16 v[110:113], v[130:133], v[218:221], v[110:113]
	v_mfma_f32_16x16x32_bf16 v[102:105], v[150:153], v[218:221], v[102:105]
	v_mfma_f32_16x16x32_bf16 v[94:97], v[130:133], v[226:229], v[94:97]
	v_mfma_f32_16x16x32_bf16 v[86:89], v[150:153], v[226:229], v[86:89]
	v_mfma_f32_16x16x32_bf16 v[78:81], v[130:133], v[234:237], v[78:81]
	v_mfma_f32_16x16x32_bf16 v[70:73], v[150:153], v[234:237], v[70:73]
	v_mfma_f32_16x16x32_bf16 v[126:129], v[146:149], v[200:203], v[126:129]
	v_mfma_f32_16x16x32_bf16 v[118:121], v[154:157], v[200:203], v[118:121]
	v_mfma_f32_16x16x32_bf16 v[110:113], v[146:149], v[222:225], v[110:113]
	v_mfma_f32_16x16x32_bf16 v[102:105], v[154:157], v[222:225], v[102:105]
	v_mfma_f32_16x16x32_bf16 v[94:97], v[146:149], v[230:233], v[94:97]
	v_mfma_f32_16x16x32_bf16 v[86:89], v[154:157], v[230:233], v[86:89]
	v_mfma_f32_16x16x32_bf16 v[78:81], v[146:149], v[238:241], v[78:81]
	v_mfma_f32_16x16x32_bf16 v[70:73], v[154:157], v[238:241], v[70:73]
	v_mfma_f32_16x16x32_bf16 v[122:125], v[180:183], v[196:199], v[122:125]
	v_mfma_f32_16x16x32_bf16 v[114:117], v[188:191], v[196:199], v[114:117]
	v_mfma_f32_16x16x32_bf16 v[106:109], v[180:183], v[218:221], v[106:109]
	v_mfma_f32_16x16x32_bf16 v[98:101], v[188:191], v[218:221], v[98:101]
	v_mfma_f32_16x16x32_bf16 v[90:93], v[180:183], v[226:229], v[90:93]
	v_mfma_f32_16x16x32_bf16 v[82:85], v[188:191], v[226:229], v[82:85]
	v_mfma_f32_16x16x32_bf16 v[74:77], v[180:183], v[234:237], v[74:77]
	v_mfma_f32_16x16x32_bf16 v[66:69], v[188:191], v[234:237], v[66:69]
	v_mfma_f32_16x16x32_bf16 v[122:125], v[184:187], v[200:203], v[122:125]
	v_mfma_f32_16x16x32_bf16 v[114:117], v[192:195], v[200:203], v[114:117]
	v_mfma_f32_16x16x32_bf16 v[106:109], v[184:187], v[222:225], v[106:109]
	v_mfma_f32_16x16x32_bf16 v[98:101], v[192:195], v[222:225], v[98:101]
	v_mfma_f32_16x16x32_bf16 v[90:93], v[184:187], v[230:233], v[90:93]
	v_mfma_f32_16x16x32_bf16 v[82:85], v[192:195], v[230:233], v[82:85]
	v_mfma_f32_16x16x32_bf16 v[74:77], v[184:187], v[238:241], v[74:77]
	v_mfma_f32_16x16x32_bf16 v[66:69], v[192:195], v[238:241], v[66:69]
	s_barrier
	s_add_i32 s40, s78, s46
	s_add_i32 m0, s40, 0xffffff80
	ds_read_b128 v[196:199], v164 offset:49152
	ds_read_b128 v[200:203], v164 offset:50176
	ds_read_b128 v[218:221], v164 offset:51200
	ds_read_b128 v[222:225], v164 offset:52224
	ds_read_b128 v[226:229], v164 offset:53248
	ds_read_b128 v[230:233], v164 offset:54272
	ds_read_b128 v[234:237], v164 offset:55296
	ds_read_b128 v[238:241], v164 offset:56320
	global_load_lds_dwordx4 v0, s[28:29] offset:128
	s_add_i32 m0, s40, 0x2000
	s_add_u32 s28, s28, 0x80080
	v_lshl_add_u64 v[158:159], v[166:167], 0, s[34:35]
	s_addc_u32 s29, s29, 0
	s_add_i32 s40, s80, s46
	global_load_lds_dwordx4 v[158:159], off
	s_mov_b32 m0, s40
	s_nop 0
	global_load_lds_dwordx4 v0, s[28:29]
	s_add_i32 m0, s40, 0x2000
	s_nop 0
	global_load_lds_dwordx4 v134, s[28:29]
	v_lshl_add_u64 v[158:159], v[242:243], 0, s[34:35]
	s_mov_b32 m0, s4
	s_nop 0
	global_load_lds_dwordx4 v[158:159], off
	v_lshl_add_u64 v[158:159], v[244:245], 0, s[34:35]
	s_mov_b32 m0, s52
	s_nop 0
	global_load_lds_dwordx4 v[158:159], off
	s_waitcnt vmcnt(8)
	s_waitcnt lgkmcnt(0)
	s_barrier
	v_mfma_f32_16x16x32_bf16 v[62:65], v[130:133], v[196:199], v[62:65]
	v_mfma_f32_16x16x32_bf16 v[54:57], v[150:153], v[196:199], v[54:57]
	v_mfma_f32_16x16x32_bf16 v[46:49], v[130:133], v[218:221], v[46:49]
	v_mfma_f32_16x16x32_bf16 v[38:41], v[150:153], v[218:221], v[38:41]
	v_mfma_f32_16x16x32_bf16 v[30:33], v[130:133], v[226:229], v[30:33]
	v_mfma_f32_16x16x32_bf16 v[22:25], v[150:153], v[226:229], v[22:25]
	v_mfma_f32_16x16x32_bf16 v[14:17], v[130:133], v[234:237], v[14:17]
	v_mfma_f32_16x16x32_bf16 v[6:9], v[150:153], v[234:237], v[6:9]
	v_mfma_f32_16x16x32_bf16 v[62:65], v[146:149], v[200:203], v[62:65]
	v_mfma_f32_16x16x32_bf16 v[54:57], v[154:157], v[200:203], v[54:57]
	v_mfma_f32_16x16x32_bf16 v[46:49], v[146:149], v[222:225], v[46:49]
	v_mfma_f32_16x16x32_bf16 v[38:41], v[154:157], v[222:225], v[38:41]
	v_mfma_f32_16x16x32_bf16 v[30:33], v[146:149], v[230:233], v[30:33]
	v_mfma_f32_16x16x32_bf16 v[22:25], v[154:157], v[230:233], v[22:25]
	v_mfma_f32_16x16x32_bf16 v[14:17], v[146:149], v[238:241], v[14:17]
	v_mfma_f32_16x16x32_bf16 v[6:9], v[154:157], v[238:241], v[6:9]
	v_mfma_f32_16x16x32_bf16 v[58:61], v[180:183], v[196:199], v[58:61]
	v_mfma_f32_16x16x32_bf16 v[50:53], v[188:191], v[196:199], v[50:53]
	v_mfma_f32_16x16x32_bf16 v[42:45], v[180:183], v[218:221], v[42:45]
	v_mfma_f32_16x16x32_bf16 v[34:37], v[188:191], v[218:221], v[34:37]
	v_mfma_f32_16x16x32_bf16 v[26:29], v[180:183], v[226:229], v[26:29]
	v_mfma_f32_16x16x32_bf16 v[18:21], v[188:191], v[226:229], v[18:21]
	v_mfma_f32_16x16x32_bf16 v[10:13], v[180:183], v[234:237], v[10:13]
	v_mfma_f32_16x16x32_bf16 v[2:5], v[188:191], v[234:237], v[2:5]
	v_mfma_f32_16x16x32_bf16 v[58:61], v[184:187], v[200:203], v[58:61]
	v_mfma_f32_16x16x32_bf16 v[50:53], v[192:195], v[200:203], v[50:53]
	v_mfma_f32_16x16x32_bf16 v[42:45], v[184:187], v[222:225], v[42:45]
	v_mfma_f32_16x16x32_bf16 v[34:37], v[192:195], v[222:225], v[34:37]
	v_mfma_f32_16x16x32_bf16 v[26:29], v[184:187], v[230:233], v[26:29]
	v_mfma_f32_16x16x32_bf16 v[18:21], v[192:195], v[230:233], v[18:21]
	v_mfma_f32_16x16x32_bf16 v[10:13], v[184:187], v[238:241], v[10:13]
	v_mfma_f32_16x16x32_bf16 v[2:5], v[192:195], v[238:241], v[2:5]
	s_barrier
	s_add_i32 s77, s77, 2
	s_add_u32 s26, s26, 0x100
	s_addc_u32 s27, s27, 0
	s_add_u32 s55, s55, 0x100
	s_addc_u32 s73, s73, 0
	s_cmp_gt_u32 s77, 29
	s_cbranch_scc0 .LBB0_165
	s_and_b64 vcc, exec, s[20:21]
	s_cbranch_vccz .LBB0_168
	s_barrier

; #define PG8_STAGE(bufoff, gbase, voff) do { _Pragma("unroll") for (int _i = 0; _i < 2; ++_i) \
;         __builtin_amdgcn_global_load_lds((const unsigned*)((const char*)(gbase) + (voff)[_i]), (PG8_LAS unsigned*)(lds + (bufoff) + ldsw + _i * 8192), 16, 0, 0); } while (0)
; #define PG8_LDA(dst, b, h) do { _Pragma("unroll") for (int m = 0; m < 4; ++m) _Pragma("unroll") for (int k = 0; k < 2; ++k) dst[m][k] = *(const PG8_LAS bf16x8*)(lds + PG8_SA(b, h) + aoff + m * 2048 + k * 1024); } while (0)
; #define PG8_LDB(dst, b, h) do { _Pragma("unroll") for (int n = 0; n < 2; ++n) _Pragma("unroll") for (int k = 0; k < 2; ++k) dst[n][k] = *(const PG8_LAS bf16x8*)(lds + PG8_SB(b, h) + boff + n * 2048 + k * 1024); } while (0)
; #define PG8_MMA(ai, bj, At, Bt) do { __builtin_amdgcn_s_setprio(1); _Pragma("unroll") for (int m = 0; m < 4; ++m) _Pragma("unroll") for (int n = 0; n < 2; ++n) _Pragma("unroll") for (int k = 0; k < 2; ++k) \
;         acc[ai][bj][m][n] = __builtin_amdgcn_mfma_f32_16x16x32_bf16(Bt[n][k], At[m][k], acc[ai][bj][m][n], 0, 0, 0); __builtin_amdgcn_s_setprio(0); } while (0)
; #define PG8_WAIT_V(n) asm volatile("s_waitcnt vmcnt(" #n ")" ::: "memory")
; #define PG8_WAIT_L(n) asm volatile("s_waitcnt lgkmcnt(" #n ")" ::: "memory")
; template <class Epi, class Sched, bool ALIGN_EPI = false, bool SP2 = false>
; __device__ __forceinline__ void gemm_phase(PG8_LAS unsigned char* lds, const Gemm g, const Sched& S, const Epi& E) {
;     ...
;             const bool last = (t == nt - 2);
;             const char* a1 = cA + (size_t)(t + 1) * kstep;
;             const char* a2 = last ? nA : cA + (size_t)(t + 2) * kstep; const char* b2 = last ? nB : cB + (size_t)(t + 2) * kstep;
;             const char* a3 = a2 + kstep; const char* b3 = b2 + kstep;
;             if (last && has_next) S.a_ready(nxt);
;             if constexpr (SP2) {
;             PG8_LDB(B0, 0, 0); PG8_LDB(B1, 0, 1); PG8_SCHED; PG8_LDA(At, 0, 0); PG8_STAGE(PG8_SA(1, 1), a1 + hstep, voffA);
;             PG8_WAIT_V(8); PG8_WAIT_L(0); PG8_BAR; PG8_MMA(0, 0, At, B0); PG8_MMA(0, 1, At, B1); PG8_BAR; PG8_SCHED;
;             PG8_LDA(At, 0, 1); PG8_STAGE(PG8_SB(0, 0), b2, voffB); PG8_STAGE(PG8_SB(0, 1), b2 + hstep, voffB); PG8_STAGE(PG8_SA(0, 0), a2, voffA);
;             PG8_WAIT_V(8); PG8_WAIT_L(0); PG8_BAR; PG8_MMA(1, 0, At, B0); PG8_MMA(1, 1, At, B1); PG8_BAR; PG8_SCHED;
.LBB0_429:
	s_add_u32 s26, s16, 0xfffc0080
	s_addc_u32 s27, s17, -1
	s_add_i32 s54, 0, 0x10000
	s_cmp_eq_u32 s78, 12
	s_cselect_b32 s29, s21, s27
	s_cselect_b32 s28, s52, s26
	v_add_u32_e32 v0, s54, v218
	s_cselect_b32 s27, s19, s77
	s_cselect_b32 s26, s53, s73
	s_add_i32 s55, 0, 0x14000
	ds_read_b128 v[52:55], v0
	ds_read_b128 v[56:59], v0 offset:1024
	ds_read_b128 v[92:95], v0 offset:2048
	ds_read_b128 v[96:99], v0 offset:3072
	v_add_u32_e32 v0, s55, v218
	ds_read_b128 v[124:127], v0
	ds_read_b128 v[128:131], v0 offset:1024
	ds_read_b128 v[148:151], v0 offset:2048
	ds_read_b128 v[152:155], v0 offset:3072
	s_add_i32 m0, s37, 0xc000
	ds_read_b128 v[164:167], v220
	ds_read_b128 v[192:195], v220 offset:1024
	ds_read_b128 v[196:199], v220 offset:2048
	ds_read_b128 v[200:203], v220 offset:3072
	ds_read_b128 v[222:225], v220 offset:4096
	ds_read_b128 v[226:229], v220 offset:5120
	ds_read_b128 v[230:233], v220 offset:6144
	ds_read_b128 v[234:237], v220 offset:7168
	global_load_lds_dwordx4 v188, s[16:17]
	s_add_i32 m0, s37, 0xe000
	s_nop 0
	global_load_lds_dwordx4 v190, s[16:17]
	s_waitcnt vmcnt(8)
	s_waitcnt lgkmcnt(0)
	s_barrier
	v_mfma_f32_16x16x32_bf16 v[88:91], v[52:55], v[164:167], v[88:91]
	v_mfma_f32_16x16x32_bf16 v[84:87], v[92:95], v[164:167], v[84:87]
	v_mfma_f32_16x16x32_bf16 v[120:123], v[52:55], v[196:199], v[120:123]
	v_mfma_f32_16x16x32_bf16 v[108:111], v[92:95], v[196:199], v[108:111]
	v_mfma_f32_16x16x32_bf16 v[136:139], v[52:55], v[222:225], v[136:139]
	v_mfma_f32_16x16x32_bf16 v[132:135], v[92:95], v[222:225], v[132:135]
	v_mfma_f32_16x16x32_bf16 v[104:107], v[52:55], v[230:233], v[104:107]
	v_mfma_f32_16x16x32_bf16 v[100:103], v[92:95], v[230:233], v[100:103]
	v_mfma_f32_16x16x32_bf16 v[88:91], v[56:59], v[192:195], v[88:91]
	v_mfma_f32_16x16x32_bf16 v[84:87], v[96:99], v[192:195], v[84:87]
	v_mfma_f32_16x16x32_bf16 v[120:123], v[56:59], v[200:203], v[120:123]
	v_mfma_f32_16x16x32_bf16 v[108:111], v[96:99], v[200:203], v[108:111]
	v_mfma_f32_16x16x32_bf16 v[136:139], v[56:59], v[226:229], v[136:139]
	v_mfma_f32_16x16x32_bf16 v[132:135], v[96:99], v[226:229], v[132:135]
	v_mfma_f32_16x16x32_bf16 v[104:107], v[56:59], v[234:237], v[104:107]
	v_mfma_f32_16x16x32_bf16 v[100:103], v[96:99], v[234:237], v[100:103]
	v_mfma_f32_16x16x32_bf16 v[160:163], v[124:127], v[164:167], v[160:163]
	v_mfma_f32_16x16x32_bf16 v[156:159], v[148:151], v[164:167], v[156:159]
	v_mfma_f32_16x16x32_bf16 v[144:147], v[124:127], v[196:199], v[144:147]
	v_mfma_f32_16x16x32_bf16 v[140:143], v[148:151], v[196:199], v[140:143]
	v_mfma_f32_16x16x32_bf16 v[116:119], v[124:127], v[222:225], v[116:119]
	v_mfma_f32_16x16x32_bf16 v[112:115], v[148:151], v[222:225], v[112:115]
	v_mfma_f32_16x16x32_bf16 v[80:83], v[124:127], v[230:233], v[80:83]
	v_mfma_f32_16x16x32_bf16 v[76:79], v[148:151], v[230:233], v[76:79]
	v_mfma_f32_16x16x32_bf16 v[160:163], v[128:131], v[192:195], v[160:163]
	v_mfma_f32_16x16x32_bf16 v[156:159], v[152:155], v[192:195], v[156:159]
	v_mfma_f32_16x16x32_bf16 v[144:147], v[128:131], v[200:203], v[144:147]
	v_mfma_f32_16x16x32_bf16 v[140:143], v[152:155], v[200:203], v[140:143]
	v_mfma_f32_16x16x32_bf16 v[116:119], v[128:131], v[226:229], v[116:119]
	v_mfma_f32_16x16x32_bf16 v[112:115], v[152:155], v[226:229], v[112:115]
	v_mfma_f32_16x16x32_bf16 v[80:83], v[128:131], v[234:237], v[80:83]
	v_mfma_f32_16x16x32_bf16 v[76:79], v[152:155], v[234:237], v[76:79]
	s_barrier
	s_add_i32 s54, s54, s2
	s_mov_b32 m0, s54
	ds_read_b128 v[164:167], v220 offset:16384
	ds_read_b128 v[192:195], v220 offset:17408
	ds_read_b128 v[196:199], v220 offset:18432
	ds_read_b128 v[200:203], v220 offset:19456
	ds_read_b128 v[222:225], v220 offset:20480
	ds_read_b128 v[226:229], v220 offset:21504
	ds_read_b128 v[230:233], v220 offset:22528
	ds_read_b128 v[234:237], v220 offset:23552
	global_load_lds_dwordx4 v184, s[26:27]
	s_add_i32 m0, s54, 0x2000
	s_add_u32 vcc_lo, s26, 0x40000
	v_lshl_add_u64 v[240:241], s[26:27], 0, v[180:181]
	s_addc_u32 vcc_hi, s27, 0
	s_add_i32 s54, s55, s2
	global_load_lds_dwordx4 v180, s[26:27]
	s_mov_b32 m0, s54
	v_lshl_add_u64 v[242:243], s[28:29], 0, v[186:187]
	global_load_lds_dwordx4 v184, vcc
	s_add_i32 m0, s54, 0x2000
	v_lshl_add_u64 v[244:245], s[28:29], 0, v[182:183]
	global_load_lds_dwordx4 v180, vcc
	s_mov_b32 m0, s37
	s_nop 0
	global_load_lds_dwordx4 v186, s[28:29]
	s_mov_b32 m0, s38
	s_nop 0
	global_load_lds_dwordx4 v182, s[28:29]
	s_waitcnt vmcnt(8)
	s_waitcnt lgkmcnt(0)
	s_barrier
	v_mfma_f32_16x16x32_bf16 v[72:75], v[52:55], v[164:167], v[72:75]
	v_mfma_f32_16x16x32_bf16 v[68:71], v[92:95], v[164:167], v[68:71]
	v_mfma_f32_16x16x32_bf16 v[48:51], v[52:55], v[196:199], v[48:51]
	v_mfma_f32_16x16x32_bf16 v[44:47], v[92:95], v[196:199], v[44:47]
	v_mfma_f32_16x16x32_bf16 v[32:35], v[52:55], v[222:225], v[32:35]
	v_mfma_f32_16x16x32_bf16 v[28:31], v[92:95], v[222:225], v[28:31]
	v_mfma_f32_16x16x32_bf16 v[16:19], v[52:55], v[230:233], v[16:19]
	v_mfma_f32_16x16x32_bf16 v[12:15], v[92:95], v[230:233], v[12:15]
	v_mfma_f32_16x16x32_bf16 v[72:75], v[56:59], v[192:195], v[72:75]
	v_mfma_f32_16x16x32_bf16 v[68:71], v[96:99], v[192:195], v[68:71]
	v_mfma_f32_16x16x32_bf16 v[48:51], v[56:59], v[200:203], v[48:51]
	v_mfma_f32_16x16x32_bf16 v[44:47], v[96:99], v[200:203], v[44:47]
	v_mfma_f32_16x16x32_bf16 v[32:35], v[56:59], v[226:229], v[32:35]
	v_mfma_f32_16x16x32_bf16 v[28:31], v[96:99], v[226:229], v[28:31]
	v_mfma_f32_16x16x32_bf16 v[16:19], v[56:59], v[234:237], v[16:19]
	v_mfma_f32_16x16x32_bf16 v[12:15], v[96:99], v[234:237], v[12:15]
	v_mfma_f32_16x16x32_bf16 v[40:43], v[124:127], v[196:199], v[40:43]
	v_mfma_f32_16x16x32_bf16 v[36:39], v[148:151], v[196:199], v[36:39]
	v_mfma_f32_16x16x32_bf16 v[24:27], v[124:127], v[222:225], v[24:27]
	v_mfma_f32_16x16x32_bf16 v[20:23], v[148:151], v[222:225], v[20:23]
	v_mfma_f32_16x16x32_bf16 v[8:11], v[124:127], v[230:233], v[8:11]
	v_mfma_f32_16x16x32_bf16 v[2:5], v[148:151], v[230:233], v[4:7]
	v_mfma_f32_16x16x32_bf16 v[52:55], v[124:127], v[164:167], v[64:67]
	v_mfma_f32_16x16x32_bf16 v[56:59], v[148:151], v[164:167], v[60:63]
	v_mfma_f32_16x16x32_bf16 v[40:43], v[128:131], v[200:203], v[40:43]
	v_mfma_f32_16x16x32_bf16 v[36:39], v[152:155], v[200:203], v[36:39]
	v_mfma_f32_16x16x32_bf16 v[24:27], v[128:131], v[226:229], v[24:27]
	v_mfma_f32_16x16x32_bf16 v[20:23], v[152:155], v[226:229], v[20:23]
	v_mfma_f32_16x16x32_bf16 v[8:11], v[128:131], v[234:237], v[8:11]
	v_mfma_f32_16x16x32_bf16 v[2:5], v[152:155], v[234:237], v[2:5]
	v_mfma_f32_16x16x32_bf16 v[52:55], v[128:131], v[192:195], v[52:55]
	v_mfma_f32_16x16x32_bf16 v[56:59], v[152:155], v[192:195], v[56:59]
	s_barrier
; #define PG8_STAGE(bufoff, gbase, voff) do { _Pragma("unroll") for (int _i = 0; _i < 2; ++_i) \
;         __builtin_amdgcn_global_load_lds((const unsigned*)((const char*)(gbase) + (voff)[_i]), (PG8_LAS unsigned*)(lds + (bufoff) + ldsw + _i * 8192), 16, 0, 0); } while (0)
; #define PG8_LDA(dst, b, h) do { _Pragma("unroll") for (int m = 0; m < 4; ++m) _Pragma("unroll") for (int k = 0; k < 2; ++k) dst[m][k] = *(const PG8_LAS bf16x8*)(lds + PG8_SA(b, h) + aoff + m * 2048 + k * 1024); } while (0)
; #define PG8_LDB(dst, b, h) do { _Pragma("unroll") for (int n = 0; n < 2; ++n) _Pragma("unroll") for (int k = 0; k < 2; ++k) dst[n][k] = *(const PG8_LAS bf16x8*)(lds + PG8_SB(b, h) + boff + n * 2048 + k * 1024); } while (0)
; #define PG8_MMA(ai, bj, At, Bt) do { __builtin_amdgcn_s_setprio(1); _Pragma("unroll") for (int m = 0; m < 4; ++m) _Pragma("unroll") for (int n = 0; n < 2; ++n) _Pragma("unroll") for (int k = 0; k < 2; ++k) \
;         acc[ai][bj][m][n] = __builtin_amdgcn_mfma_f32_16x16x32_bf16(Bt[n][k], At[m][k], acc[ai][bj][m][n], 0, 0, 0); __builtin_amdgcn_s_setprio(0); } while (0)
; #define PG8_WAIT_V(n) asm volatile("s_waitcnt vmcnt(" #n ")" ::: "memory")
; #define PG8_WAIT_L(n) asm volatile("s_waitcnt lgkmcnt(" #n ")" ::: "memory")
; #define PG8_BAR __builtin_amdgcn_s_barrier()
; #define PG8_SCHED __builtin_amdgcn_sched_barrier(0)
; template <class Epi, class Sched, bool ALIGN_EPI = false, bool SP2 = false>
; __device__ __forceinline__ void gemm_phase(PG8_LAS unsigned char* lds, const Gemm g, const Sched& S, const Epi& E) {
;     ...
;             PG8_LDB(B0, 1, 0); PG8_LDB(B1, 1, 1); PG8_SCHED; PG8_LDA(At, 1, 0); PG8_STAGE(PG8_SA(0, 1), a2 + hstep, voffA);
;             PG8_WAIT_V(8); PG8_WAIT_L(0); PG8_BAR; PG8_MMA(0, 0, At, B0); PG8_MMA(0, 1, At, B1); PG8_BAR; PG8_SCHED;
;             PG8_LDA(At, 1, 1); PG8_STAGE(PG8_SB(1, 0), b3, voffB); PG8_STAGE(PG8_SB(1, 1), b3 + hstep, voffB); PG8_STAGE(PG8_SA(1, 0), a3, voffA);
;             PG8_WAIT_V(8); PG8_WAIT_L(0); PG8_BAR; PG8_MMA(1, 0, At, B0); PG8_MMA(1, 1, At, B1); PG8_BAR; PG8_SCHED;
;     ...
;         if constexpr (ALIGN_EPI) { if (wr == 0) PG8_BAR; }
	s_add_i32 s54, 0, 0x18000
	v_add_u32_e32 v0, s54, v218
	s_add_i32 s55, 0, 0x1c000
	ds_read_b128 v[60:63], v0
	ds_read_b128 v[64:67], v0 offset:1024
	ds_read_b128 v[92:95], v0 offset:2048
	ds_read_b128 v[96:99], v0 offset:3072
	v_add_u32_e32 v0, s55, v218
	ds_read_b128 v[124:127], v0
	ds_read_b128 v[128:131], v0 offset:1024
	ds_read_b128 v[148:151], v0 offset:2048
	ds_read_b128 v[152:155], v0 offset:3072
	s_add_u32 s28, s28, 0x40000
	s_addc_u32 s29, s29, 0
	s_mov_b32 m0, s39
	ds_read_b128 v[164:167], v220 offset:32768
	ds_read_b128 v[192:195], v220 offset:33792
	ds_read_b128 v[196:199], v220 offset:34816
	ds_read_b128 v[200:203], v220 offset:35840
	ds_read_b128 v[222:225], v220 offset:36864
	ds_read_b128 v[226:229], v220 offset:37888
	ds_read_b128 v[230:233], v220 offset:38912
	ds_read_b128 v[234:237], v220 offset:39936
	global_load_lds_dwordx4 v186, s[28:29]
	s_mov_b32 m0, s44
	s_nop 0
	global_load_lds_dwordx4 v182, s[28:29]
	s_waitcnt vmcnt(8)
	s_waitcnt lgkmcnt(0)
	s_barrier
	v_mfma_f32_16x16x32_bf16 v[88:91], v[60:63], v[164:167], v[88:91]
	v_mfma_f32_16x16x32_bf16 v[84:87], v[92:95], v[164:167], v[84:87]
	v_mfma_f32_16x16x32_bf16 v[120:123], v[60:63], v[196:199], v[120:123]
	v_mfma_f32_16x16x32_bf16 v[108:111], v[92:95], v[196:199], v[108:111]
	v_mfma_f32_16x16x32_bf16 v[136:139], v[60:63], v[222:225], v[136:139]
	v_mfma_f32_16x16x32_bf16 v[132:135], v[92:95], v[222:225], v[132:135]
	v_mfma_f32_16x16x32_bf16 v[104:107], v[60:63], v[230:233], v[104:107]
	v_mfma_f32_16x16x32_bf16 v[100:103], v[92:95], v[230:233], v[100:103]
	v_mfma_f32_16x16x32_bf16 v[88:91], v[64:67], v[192:195], v[88:91]
	v_mfma_f32_16x16x32_bf16 v[84:87], v[96:99], v[192:195], v[84:87]
	v_mfma_f32_16x16x32_bf16 v[120:123], v[64:67], v[200:203], v[120:123]
	v_mfma_f32_16x16x32_bf16 v[108:111], v[96:99], v[200:203], v[108:111]
	v_mfma_f32_16x16x32_bf16 v[136:139], v[64:67], v[226:229], v[136:139]
	v_mfma_f32_16x16x32_bf16 v[132:135], v[96:99], v[226:229], v[132:135]
	v_mfma_f32_16x16x32_bf16 v[104:107], v[64:67], v[234:237], v[104:107]
	v_mfma_f32_16x16x32_bf16 v[100:103], v[96:99], v[234:237], v[100:103]
	v_mfma_f32_16x16x32_bf16 v[160:163], v[124:127], v[164:167], v[160:163]
	v_mfma_f32_16x16x32_bf16 v[156:159], v[148:151], v[164:167], v[156:159]
	v_mfma_f32_16x16x32_bf16 v[144:147], v[124:127], v[196:199], v[144:147]
	v_mfma_f32_16x16x32_bf16 v[140:143], v[148:151], v[196:199], v[140:143]
	v_mfma_f32_16x16x32_bf16 v[116:119], v[124:127], v[222:225], v[116:119]
	v_mfma_f32_16x16x32_bf16 v[112:115], v[148:151], v[222:225], v[112:115]
	v_mfma_f32_16x16x32_bf16 v[80:83], v[124:127], v[230:233], v[80:83]
	v_mfma_f32_16x16x32_bf16 v[76:79], v[148:151], v[230:233], v[76:79]
	v_mfma_f32_16x16x32_bf16 v[160:163], v[128:131], v[192:195], v[160:163]
	v_mfma_f32_16x16x32_bf16 v[156:159], v[152:155], v[192:195], v[156:159]
	v_mfma_f32_16x16x32_bf16 v[144:147], v[128:131], v[200:203], v[144:147]
	v_mfma_f32_16x16x32_bf16 v[140:143], v[152:155], v[200:203], v[140:143]
	v_mfma_f32_16x16x32_bf16 v[116:119], v[128:131], v[226:229], v[116:119]
	v_mfma_f32_16x16x32_bf16 v[112:115], v[152:155], v[226:229], v[112:115]
	v_mfma_f32_16x16x32_bf16 v[80:83], v[128:131], v[234:237], v[80:83]
	v_mfma_f32_16x16x32_bf16 v[76:79], v[152:155], v[234:237], v[76:79]
	s_barrier
	s_add_i32 s28, s54, s2
	s_add_i32 m0, s28, 0xffffff80
	ds_read_b128 v[164:167], v220 offset:49152
	ds_read_b128 v[192:195], v220 offset:50176
	ds_read_b128 v[196:199], v220 offset:51200
	ds_read_b128 v[200:203], v220 offset:52224
	ds_read_b128 v[222:225], v220 offset:53248
	ds_read_b128 v[226:229], v220 offset:54272
	ds_read_b128 v[230:233], v220 offset:55296
	ds_read_b128 v[234:237], v220 offset:56320
	global_load_lds_dwordx4 v184, s[26:27] offset:128
	s_add_i32 m0, s28, 0x2000
	s_add_u32 s26, s26, 0x40080
	v_lshl_add_u64 v[6:7], v[240:241], 0, s[34:35]
	s_addc_u32 s27, s27, 0
	s_add_i32 s28, s55, s2
	global_load_lds_dwordx4 v[6:7], off
	s_mov_b32 m0, s28
	s_nop 0
	global_load_lds_dwordx4 v184, s[26:27]
	s_add_i32 m0, s28, 0x2000
	s_nop 0
	global_load_lds_dwordx4 v180, s[26:27]
	v_lshl_add_u64 v[6:7], v[242:243], 0, s[34:35]
	s_mov_b32 m0, s47
	s_nop 0
	global_load_lds_dwordx4 v[6:7], off
	v_lshl_add_u64 v[6:7], v[244:245], 0, s[34:35]
	s_mov_b32 m0, s48
	s_nop 0
	global_load_lds_dwordx4 v[6:7], off
	s_waitcnt vmcnt(8)
	s_waitcnt lgkmcnt(0)
	s_barrier
	v_mfma_f32_16x16x32_bf16 v[72:75], v[60:63], v[164:167], v[72:75]
	v_mfma_f32_16x16x32_bf16 v[68:71], v[92:95], v[164:167], v[68:71]
	v_mfma_f32_16x16x32_bf16 v[48:51], v[60:63], v[196:199], v[48:51]
	v_mfma_f32_16x16x32_bf16 v[44:47], v[92:95], v[196:199], v[44:47]
	v_mfma_f32_16x16x32_bf16 v[32:35], v[60:63], v[222:225], v[32:35]
	v_mfma_f32_16x16x32_bf16 v[28:31], v[92:95], v[222:225], v[28:31]
	v_mfma_f32_16x16x32_bf16 v[16:19], v[60:63], v[230:233], v[16:19]
	v_mfma_f32_16x16x32_bf16 v[12:15], v[92:95], v[230:233], v[12:15]
	v_mfma_f32_16x16x32_bf16 v[72:75], v[64:67], v[192:195], v[72:75]
	v_mfma_f32_16x16x32_bf16 v[68:71], v[96:99], v[192:195], v[68:71]
	v_mfma_f32_16x16x32_bf16 v[48:51], v[64:67], v[200:203], v[48:51]
	v_mfma_f32_16x16x32_bf16 v[44:47], v[96:99], v[200:203], v[44:47]
	v_mfma_f32_16x16x32_bf16 v[32:35], v[64:67], v[226:229], v[32:35]
	v_mfma_f32_16x16x32_bf16 v[28:31], v[96:99], v[226:229], v[28:31]
	v_mfma_f32_16x16x32_bf16 v[16:19], v[64:67], v[234:237], v[16:19]
	v_mfma_f32_16x16x32_bf16 v[12:15], v[96:99], v[234:237], v[12:15]
	v_mfma_f32_16x16x32_bf16 v[52:55], v[124:127], v[164:167], v[52:55]
	v_mfma_f32_16x16x32_bf16 v[64:67], v[128:131], v[192:195], v[52:55]
	v_mfma_f32_16x16x32_bf16 v[52:55], v[148:151], v[164:167], v[56:59]
	v_mfma_f32_16x16x32_bf16 v[40:43], v[124:127], v[196:199], v[40:43]
	v_mfma_f32_16x16x32_bf16 v[36:39], v[148:151], v[196:199], v[36:39]
	v_mfma_f32_16x16x32_bf16 v[24:27], v[124:127], v[222:225], v[24:27]
	v_mfma_f32_16x16x32_bf16 v[20:23], v[148:151], v[222:225], v[20:23]
	v_mfma_f32_16x16x32_bf16 v[6:9], v[124:127], v[230:233], v[8:11]
	v_mfma_f32_16x16x32_bf16 v[2:5], v[148:151], v[230:233], v[2:5]
	v_mfma_f32_16x16x32_bf16 v[60:63], v[152:155], v[192:195], v[52:55]
	v_mfma_f32_16x16x32_bf16 v[40:43], v[128:131], v[200:203], v[40:43]
	v_mfma_f32_16x16x32_bf16 v[36:39], v[152:155], v[200:203], v[36:39]
	v_mfma_f32_16x16x32_bf16 v[24:27], v[128:131], v[226:229], v[24:27]
	v_mfma_f32_16x16x32_bf16 v[20:23], v[152:155], v[226:229], v[20:23]
	v_mfma_f32_16x16x32_bf16 v[8:11], v[128:131], v[234:237], v[6:9]
	v_mfma_f32_16x16x32_bf16 v[4:7], v[152:155], v[234:237], v[2:5]
	s_barrier
	s_add_i32 s78, s78, 2
	s_add_u32 s16, s16, 0x100
	s_addc_u32 s17, s17, 0
	s_add_u32 s73, s73, 0x100
	s_addc_u32 s77, s77, 0
	s_cmp_gt_u32 s78, 13
	s_cbranch_scc0 .LBB0_429
	s_and_b64 vcc, exec, s[6:7]
	s_cbranch_vccz .LBB0_432
	s_barrier

; #define PG8_STAGE(bufoff, gbase, voff) do { _Pragma("unroll") for (int _i = 0; _i < 2; ++_i) \
;         __builtin_amdgcn_global_load_lds((const unsigned*)((const char*)(gbase) + (voff)[_i]), (PG8_LAS unsigned*)(lds + (bufoff) + ldsw + _i * 8192), 16, 0, 0); } while (0)
; #define PG8_LDA(dst, b, h) do { _Pragma("unroll") for (int m = 0; m < 4; ++m) _Pragma("unroll") for (int k = 0; k < 2; ++k) dst[m][k] = *(const PG8_LAS bf16x8*)(lds + PG8_SA(b, h) + aoff + m * 2048 + k * 1024); } while (0)
; #define PG8_LDB(dst, b, h) do { _Pragma("unroll") for (int n = 0; n < 2; ++n) _Pragma("unroll") for (int k = 0; k < 2; ++k) dst[n][k] = *(const PG8_LAS bf16x8*)(lds + PG8_SB(b, h) + boff + n * 2048 + k * 1024); } while (0)
; #define PG8_MMA(ai, bj, At, Bt) do { __builtin_amdgcn_s_setprio(1); _Pragma("unroll") for (int m = 0; m < 4; ++m) _Pragma("unroll") for (int n = 0; n < 2; ++n) _Pragma("unroll") for (int k = 0; k < 2; ++k) \
;         acc[ai][bj][m][n] = __builtin_amdgcn_mfma_f32_16x16x32_bf16(Bt[n][k], At[m][k], acc[ai][bj][m][n], 0, 0, 0); __builtin_amdgcn_s_setprio(0); } while (0)
; #define PG8_WAIT_V(n) asm volatile("s_waitcnt vmcnt(" #n ")" ::: "memory")
; #define PG8_WAIT_L(n) asm volatile("s_waitcnt lgkmcnt(" #n ")" ::: "memory")
; template <class Epi, class Sched, bool ALIGN_EPI = false, bool SP2 = false>
; __device__ __forceinline__ void gemm_phase(PG8_LAS unsigned char* lds, const Gemm g, const Sched& S, const Epi& E) {
;     ...
;             const bool last = (t == nt - 2);
;             const char* a1 = cA + (size_t)(t + 1) * kstep;
;             const char* a2 = last ? nA : cA + (size_t)(t + 2) * kstep; const char* b2 = last ? nB : cB + (size_t)(t + 2) * kstep;
;             const char* a3 = a2 + kstep; const char* b3 = b2 + kstep;
;             if (last && has_next) S.a_ready(nxt);
;             if constexpr (SP2) {
;             PG8_LDB(B0, 0, 0); PG8_LDB(B1, 0, 1); PG8_SCHED; PG8_LDA(At, 0, 0); PG8_STAGE(PG8_SA(1, 1), a1 + hstep, voffA);
;             PG8_WAIT_V(8); PG8_WAIT_L(0); PG8_BAR; PG8_MMA(0, 0, At, B0); PG8_MMA(0, 1, At, B1); PG8_BAR; PG8_SCHED;
;             PG8_LDA(At, 0, 1); PG8_STAGE(PG8_SB(0, 0), b2, voffB); PG8_STAGE(PG8_SB(0, 1), b2 + hstep, voffB); PG8_STAGE(PG8_SA(0, 0), a2, voffA);
;             PG8_WAIT_V(8); PG8_WAIT_L(0); PG8_BAR; PG8_MMA(1, 0, At, B0); PG8_MMA(1, 1, At, B1); PG8_BAR; PG8_SCHED;
.LBB0_553:
	s_add_u32 s26, s16, 0xfff80080
	s_addc_u32 s27, s17, -1
	s_add_i32 s54, 0, 0x10000
	s_cmp_eq_u32 vcc_hi, 28
	s_cselect_b32 s29, s23, s27
	s_cselect_b32 s28, s38, s26
	s_cselect_b32 s27, s21, vcc_lo
	s_cselect_b32 s26, s39, s78
	s_add_i32 s80, 0, 0x14000
	v_add_u32_e32 v134, s54, v191
	v_add_u32_e32 v166, s80, v191
	ds_read_b128 v[114:117], v134
	ds_read_b128 v[118:121], v134 offset:1024
	ds_read_b128 v[122:125], v134 offset:2048
	ds_read_b128 v[134:137], v134 offset:3072
	ds_read_b128 v[146:149], v166
	ds_read_b128 v[150:153], v166 offset:1024
	ds_read_b128 v[180:183], v166 offset:2048
	ds_read_b128 v[184:187], v166 offset:3072
	s_add_i32 m0, s48, 0xc000
	ds_read_b128 v[196:199], v194
	ds_read_b128 v[200:203], v194 offset:1024
	ds_read_b128 v[218:221], v194 offset:2048
	ds_read_b128 v[222:225], v194 offset:3072
	ds_read_b128 v[226:229], v194 offset:4096
	ds_read_b128 v[230:233], v194 offset:5120
	ds_read_b128 v[234:237], v194 offset:6144
	ds_read_b128 v[238:241], v194 offset:7168
	global_load_lds_dwordx4 v162, s[16:17]
	s_add_i32 m0, s48, 0xe000
	s_nop 0
	global_load_lds_dwordx4 v164, s[16:17]
	s_waitcnt vmcnt(8)
	s_waitcnt lgkmcnt(0)
	s_barrier
	v_mfma_f32_16x16x32_bf16 v[142:145], v[114:117], v[196:199], v[142:145]
	v_mfma_f32_16x16x32_bf16 v[138:141], v[122:125], v[196:199], v[138:141]
	v_mfma_f32_16x16x32_bf16 v[110:113], v[114:117], v[218:221], v[110:113]
	v_mfma_f32_16x16x32_bf16 v[106:109], v[122:125], v[218:221], v[106:109]
	v_mfma_f32_16x16x32_bf16 v[94:97], v[114:117], v[226:229], v[94:97]
	v_mfma_f32_16x16x32_bf16 v[90:93], v[122:125], v[226:229], v[90:93]
	v_mfma_f32_16x16x32_bf16 v[78:81], v[114:117], v[234:237], v[78:81]
	v_mfma_f32_16x16x32_bf16 v[74:77], v[122:125], v[234:237], v[74:77]
	v_mfma_f32_16x16x32_bf16 v[142:145], v[118:121], v[200:203], v[142:145]
	v_mfma_f32_16x16x32_bf16 v[138:141], v[134:137], v[200:203], v[138:141]
	v_mfma_f32_16x16x32_bf16 v[110:113], v[118:121], v[222:225], v[110:113]
	v_mfma_f32_16x16x32_bf16 v[106:109], v[134:137], v[222:225], v[106:109]
	v_mfma_f32_16x16x32_bf16 v[94:97], v[118:121], v[230:233], v[94:97]
	v_mfma_f32_16x16x32_bf16 v[90:93], v[134:137], v[230:233], v[90:93]
	v_mfma_f32_16x16x32_bf16 v[78:81], v[118:121], v[238:241], v[78:81]
	v_mfma_f32_16x16x32_bf16 v[74:77], v[134:137], v[238:241], v[74:77]
	v_mfma_f32_16x16x32_bf16 v[130:133], v[146:149], v[196:199], v[130:133]
	v_mfma_f32_16x16x32_bf16 v[126:129], v[180:183], v[196:199], v[126:129]
	v_mfma_f32_16x16x32_bf16 v[102:105], v[146:149], v[218:221], v[102:105]
	v_mfma_f32_16x16x32_bf16 v[98:101], v[180:183], v[218:221], v[98:101]
	v_mfma_f32_16x16x32_bf16 v[86:89], v[146:149], v[226:229], v[86:89]
	v_mfma_f32_16x16x32_bf16 v[82:85], v[180:183], v[226:229], v[82:85]
	v_mfma_f32_16x16x32_bf16 v[70:73], v[146:149], v[234:237], v[70:73]
	v_mfma_f32_16x16x32_bf16 v[66:69], v[180:183], v[234:237], v[66:69]
	v_mfma_f32_16x16x32_bf16 v[130:133], v[150:153], v[200:203], v[130:133]
	v_mfma_f32_16x16x32_bf16 v[126:129], v[184:187], v[200:203], v[126:129]
	v_mfma_f32_16x16x32_bf16 v[102:105], v[150:153], v[222:225], v[102:105]
	v_mfma_f32_16x16x32_bf16 v[98:101], v[184:187], v[222:225], v[98:101]
	v_mfma_f32_16x16x32_bf16 v[86:89], v[150:153], v[230:233], v[86:89]
	v_mfma_f32_16x16x32_bf16 v[82:85], v[184:187], v[230:233], v[82:85]
	v_mfma_f32_16x16x32_bf16 v[70:73], v[150:153], v[238:241], v[70:73]
	v_mfma_f32_16x16x32_bf16 v[66:69], v[184:187], v[238:241], v[66:69]
	s_barrier
	s_add_i32 s54, s54, s2
	s_mov_b32 m0, s54
	ds_read_b128 v[196:199], v194 offset:16384
	ds_read_b128 v[200:203], v194 offset:17408
	ds_read_b128 v[218:221], v194 offset:18432
	ds_read_b128 v[222:225], v194 offset:19456
	ds_read_b128 v[226:229], v194 offset:20480
	ds_read_b128 v[230:233], v194 offset:21504
	ds_read_b128 v[234:237], v194 offset:22528
	ds_read_b128 v[238:241], v194 offset:23552
	global_load_lds_dwordx4 v0, s[26:27]
	s_add_i32 m0, s54, 0x2000
	s_add_u32 s54, s26, 0x80000
	v_lshl_add_u64 v[188:189], s[26:27], 0, v[154:155]
	s_addc_u32 s55, s27, 0
	s_add_i32 s80, s80, s2
	global_load_lds_dwordx4 v154, s[26:27]
	s_mov_b32 m0, s80
	v_lshl_add_u64 v[244:245], s[28:29], 0, v[156:157]
	global_load_lds_dwordx4 v0, s[54:55]
	s_add_i32 m0, s80, 0x2000
	s_nop 0
	global_load_lds_dwordx4 v154, s[54:55]
	v_lshl_add_u64 v[242:243], s[28:29], 0, v[158:159]
	s_mov_b32 m0, s48
	s_nop 0
	global_load_lds_dwordx4 v158, s[28:29]
	s_mov_b32 m0, s49
	s_nop 0
	global_load_lds_dwordx4 v156, s[28:29]
	s_waitcnt vmcnt(8)
	s_waitcnt lgkmcnt(0)
	s_barrier
	v_mfma_f32_16x16x32_bf16 v[62:65], v[114:117], v[196:199], v[62:65]
	v_mfma_f32_16x16x32_bf16 v[58:61], v[122:125], v[196:199], v[58:61]
	v_mfma_f32_16x16x32_bf16 v[46:49], v[114:117], v[218:221], v[46:49]
	v_mfma_f32_16x16x32_bf16 v[42:45], v[122:125], v[218:221], v[42:45]
	v_mfma_f32_16x16x32_bf16 v[30:33], v[114:117], v[226:229], v[30:33]
	v_mfma_f32_16x16x32_bf16 v[26:29], v[122:125], v[226:229], v[26:29]
	v_mfma_f32_16x16x32_bf16 v[14:17], v[114:117], v[234:237], v[14:17]
	v_mfma_f32_16x16x32_bf16 v[10:13], v[122:125], v[234:237], v[10:13]
	v_mfma_f32_16x16x32_bf16 v[62:65], v[118:121], v[200:203], v[62:65]
	v_mfma_f32_16x16x32_bf16 v[58:61], v[134:137], v[200:203], v[58:61]
	v_mfma_f32_16x16x32_bf16 v[46:49], v[118:121], v[222:225], v[46:49]
	v_mfma_f32_16x16x32_bf16 v[42:45], v[134:137], v[222:225], v[42:45]
	v_mfma_f32_16x16x32_bf16 v[30:33], v[118:121], v[230:233], v[30:33]
	v_mfma_f32_16x16x32_bf16 v[26:29], v[134:137], v[230:233], v[26:29]
	v_mfma_f32_16x16x32_bf16 v[14:17], v[118:121], v[238:241], v[14:17]
	v_mfma_f32_16x16x32_bf16 v[10:13], v[134:137], v[238:241], v[10:13]
	v_mfma_f32_16x16x32_bf16 v[54:57], v[146:149], v[196:199], v[54:57]
	v_mfma_f32_16x16x32_bf16 v[50:53], v[180:183], v[196:199], v[50:53]
	v_mfma_f32_16x16x32_bf16 v[38:41], v[146:149], v[218:221], v[38:41]
	v_mfma_f32_16x16x32_bf16 v[34:37], v[180:183], v[218:221], v[34:37]
	v_mfma_f32_16x16x32_bf16 v[22:25], v[146:149], v[226:229], v[22:25]
	v_mfma_f32_16x16x32_bf16 v[18:21], v[180:183], v[226:229], v[18:21]
	v_mfma_f32_16x16x32_bf16 v[6:9], v[146:149], v[234:237], v[6:9]
	v_mfma_f32_16x16x32_bf16 v[2:5], v[180:183], v[234:237], v[2:5]
	v_mfma_f32_16x16x32_bf16 v[54:57], v[150:153], v[200:203], v[54:57]
	v_mfma_f32_16x16x32_bf16 v[50:53], v[184:187], v[200:203], v[50:53]
	v_mfma_f32_16x16x32_bf16 v[38:41], v[150:153], v[222:225], v[38:41]
	v_mfma_f32_16x16x32_bf16 v[34:37], v[184:187], v[222:225], v[34:37]
	v_mfma_f32_16x16x32_bf16 v[22:25], v[150:153], v[230:233], v[22:25]
	v_mfma_f32_16x16x32_bf16 v[18:21], v[184:187], v[230:233], v[18:21]
	v_mfma_f32_16x16x32_bf16 v[6:9], v[150:153], v[238:241], v[6:9]
	v_mfma_f32_16x16x32_bf16 v[2:5], v[184:187], v[238:241], v[2:5]
	s_barrier
; #define PG8_STAGE(bufoff, gbase, voff) do { _Pragma("unroll") for (int _i = 0; _i < 2; ++_i) \
;         __builtin_amdgcn_global_load_lds((const unsigned*)((const char*)(gbase) + (voff)[_i]), (PG8_LAS unsigned*)(lds + (bufoff) + ldsw + _i * 8192), 16, 0, 0); } while (0)
; #define PG8_LDA(dst, b, h) do { _Pragma("unroll") for (int m = 0; m < 4; ++m) _Pragma("unroll") for (int k = 0; k < 2; ++k) dst[m][k] = *(const PG8_LAS bf16x8*)(lds + PG8_SA(b, h) + aoff + m * 2048 + k * 1024); } while (0)
; #define PG8_LDB(dst, b, h) do { _Pragma("unroll") for (int n = 0; n < 2; ++n) _Pragma("unroll") for (int k = 0; k < 2; ++k) dst[n][k] = *(const PG8_LAS bf16x8*)(lds + PG8_SB(b, h) + boff + n * 2048 + k * 1024); } while (0)
; #define PG8_MMA(ai, bj, At, Bt) do { __builtin_amdgcn_s_setprio(1); _Pragma("unroll") for (int m = 0; m < 4; ++m) _Pragma("unroll") for (int n = 0; n < 2; ++n) _Pragma("unroll") for (int k = 0; k < 2; ++k) \
;         acc[ai][bj][m][n] = __builtin_amdgcn_mfma_f32_16x16x32_bf16(Bt[n][k], At[m][k], acc[ai][bj][m][n], 0, 0, 0); __builtin_amdgcn_s_setprio(0); } while (0)
; #define PG8_WAIT_V(n) asm volatile("s_waitcnt vmcnt(" #n ")" ::: "memory")
; #define PG8_WAIT_L(n) asm volatile("s_waitcnt lgkmcnt(" #n ")" ::: "memory")
; #define PG8_BAR __builtin_amdgcn_s_barrier()
; #define PG8_SCHED __builtin_amdgcn_sched_barrier(0)
; template <class Epi, class Sched, bool ALIGN_EPI = false, bool SP2 = false>
; __device__ __forceinline__ void gemm_phase(PG8_LAS unsigned char* lds, const Gemm g, const Sched& S, const Epi& E) {
;     ...
;             PG8_LDB(B0, 1, 0); PG8_LDB(B1, 1, 1); PG8_SCHED; PG8_LDA(At, 1, 0); PG8_STAGE(PG8_SA(0, 1), a2 + hstep, voffA);
;             PG8_WAIT_V(8); PG8_WAIT_L(0); PG8_BAR; PG8_MMA(0, 0, At, B0); PG8_MMA(0, 1, At, B1); PG8_BAR; PG8_SCHED;
;             PG8_LDA(At, 1, 1); PG8_STAGE(PG8_SB(1, 0), b3, voffB); PG8_STAGE(PG8_SB(1, 1), b3 + hstep, voffB); PG8_STAGE(PG8_SA(1, 0), a3, voffA);
;             PG8_WAIT_V(8); PG8_WAIT_L(0); PG8_BAR; PG8_MMA(1, 0, At, B0); PG8_MMA(1, 1, At, B1); PG8_BAR; PG8_SCHED;
;     ...
;         if constexpr (ALIGN_EPI) { if (wr == 0) PG8_BAR; }
	s_add_i32 s54, 0, 0x18000
	s_add_i32 s55, 0, 0x1c000
	v_add_u32_e32 v134, s54, v191
	v_add_u32_e32 v184, s55, v191
	ds_read_b128 v[114:117], v134
	ds_read_b128 v[118:121], v134 offset:1024
	ds_read_b128 v[122:125], v134 offset:2048
	ds_read_b128 v[134:137], v134 offset:3072
	ds_read_b128 v[146:149], v184
	ds_read_b128 v[150:153], v184 offset:1024
	ds_read_b128 v[180:183], v184 offset:2048
	ds_read_b128 v[184:187], v184 offset:3072
	s_add_u32 s28, s28, 0x80000
	s_addc_u32 s29, s29, 0
	s_mov_b32 m0, s50
	ds_read_b128 v[196:199], v194 offset:32768
	ds_read_b128 v[200:203], v194 offset:33792
	ds_read_b128 v[218:221], v194 offset:34816
	ds_read_b128 v[222:225], v194 offset:35840
	ds_read_b128 v[226:229], v194 offset:36864
	ds_read_b128 v[230:233], v194 offset:37888
	ds_read_b128 v[234:237], v194 offset:38912
	ds_read_b128 v[238:241], v194 offset:39936
	global_load_lds_dwordx4 v158, s[28:29]
	s_mov_b32 m0, s51
	s_nop 0
	global_load_lds_dwordx4 v156, s[28:29]
	s_waitcnt vmcnt(8)
	s_waitcnt lgkmcnt(0)
	s_barrier
	v_mfma_f32_16x16x32_bf16 v[142:145], v[114:117], v[196:199], v[142:145]
	v_mfma_f32_16x16x32_bf16 v[138:141], v[122:125], v[196:199], v[138:141]
	v_mfma_f32_16x16x32_bf16 v[110:113], v[114:117], v[218:221], v[110:113]
	v_mfma_f32_16x16x32_bf16 v[106:109], v[122:125], v[218:221], v[106:109]
	v_mfma_f32_16x16x32_bf16 v[94:97], v[114:117], v[226:229], v[94:97]
	v_mfma_f32_16x16x32_bf16 v[90:93], v[122:125], v[226:229], v[90:93]
	v_mfma_f32_16x16x32_bf16 v[78:81], v[114:117], v[234:237], v[78:81]
	v_mfma_f32_16x16x32_bf16 v[74:77], v[122:125], v[234:237], v[74:77]
	v_mfma_f32_16x16x32_bf16 v[142:145], v[118:121], v[200:203], v[142:145]
	v_mfma_f32_16x16x32_bf16 v[138:141], v[134:137], v[200:203], v[138:141]
	v_mfma_f32_16x16x32_bf16 v[110:113], v[118:121], v[222:225], v[110:113]
	v_mfma_f32_16x16x32_bf16 v[106:109], v[134:137], v[222:225], v[106:109]
	v_mfma_f32_16x16x32_bf16 v[94:97], v[118:121], v[230:233], v[94:97]
	v_mfma_f32_16x16x32_bf16 v[90:93], v[134:137], v[230:233], v[90:93]
	v_mfma_f32_16x16x32_bf16 v[78:81], v[118:121], v[238:241], v[78:81]
	v_mfma_f32_16x16x32_bf16 v[74:77], v[134:137], v[238:241], v[74:77]
	v_mfma_f32_16x16x32_bf16 v[130:133], v[146:149], v[196:199], v[130:133]
	v_mfma_f32_16x16x32_bf16 v[126:129], v[180:183], v[196:199], v[126:129]
	v_mfma_f32_16x16x32_bf16 v[102:105], v[146:149], v[218:221], v[102:105]
	v_mfma_f32_16x16x32_bf16 v[98:101], v[180:183], v[218:221], v[98:101]
	v_mfma_f32_16x16x32_bf16 v[86:89], v[146:149], v[226:229], v[86:89]
	v_mfma_f32_16x16x32_bf16 v[82:85], v[180:183], v[226:229], v[82:85]
	v_mfma_f32_16x16x32_bf16 v[70:73], v[146:149], v[234:237], v[70:73]
	v_mfma_f32_16x16x32_bf16 v[66:69], v[180:183], v[234:237], v[66:69]
	v_mfma_f32_16x16x32_bf16 v[130:133], v[150:153], v[200:203], v[130:133]
	v_mfma_f32_16x16x32_bf16 v[126:129], v[184:187], v[200:203], v[126:129]
	v_mfma_f32_16x16x32_bf16 v[102:105], v[150:153], v[222:225], v[102:105]
	v_mfma_f32_16x16x32_bf16 v[98:101], v[184:187], v[222:225], v[98:101]
	v_mfma_f32_16x16x32_bf16 v[86:89], v[150:153], v[230:233], v[86:89]
	v_mfma_f32_16x16x32_bf16 v[82:85], v[184:187], v[230:233], v[82:85]
	v_mfma_f32_16x16x32_bf16 v[70:73], v[150:153], v[238:241], v[70:73]
	v_mfma_f32_16x16x32_bf16 v[66:69], v[184:187], v[238:241], v[66:69]
	s_barrier
	s_add_i32 s28, s54, s2
	s_add_i32 m0, s28, 0xffffff80
	ds_read_b128 v[196:199], v194 offset:49152
	ds_read_b128 v[200:203], v194 offset:50176
	ds_read_b128 v[218:221], v194 offset:51200
	ds_read_b128 v[222:225], v194 offset:52224
	ds_read_b128 v[226:229], v194 offset:53248
	ds_read_b128 v[230:233], v194 offset:54272
	ds_read_b128 v[234:237], v194 offset:55296
	ds_read_b128 v[238:241], v194 offset:56320
	global_load_lds_dwordx4 v0, s[26:27] offset:128
	s_add_i32 m0, s28, 0x2000
	s_add_u32 s26, s26, 0x80080
	v_lshl_add_u64 v[166:167], v[188:189], 0, s[34:35]
	s_addc_u32 s27, s27, 0
	s_add_i32 s28, s55, s2
	global_load_lds_dwordx4 v[166:167], off
	s_mov_b32 m0, s28
	s_nop 0
	global_load_lds_dwordx4 v0, s[26:27]
	s_add_i32 m0, s28, 0x2000
	s_nop 0
	global_load_lds_dwordx4 v154, s[26:27]
	v_lshl_add_u64 v[166:167], v[242:243], 0, s[34:35]
	s_mov_b32 m0, s53
	s_nop 0
	global_load_lds_dwordx4 v[166:167], off
	v_lshl_add_u64 v[166:167], v[244:245], 0, s[34:35]
	s_mov_b32 m0, s73
	s_nop 0
	global_load_lds_dwordx4 v[166:167], off
	s_waitcnt vmcnt(8)
	s_waitcnt lgkmcnt(0)
	s_barrier
	v_mfma_f32_16x16x32_bf16 v[62:65], v[114:117], v[196:199], v[62:65]
	v_mfma_f32_16x16x32_bf16 v[58:61], v[122:125], v[196:199], v[58:61]
	v_mfma_f32_16x16x32_bf16 v[46:49], v[114:117], v[218:221], v[46:49]
	v_mfma_f32_16x16x32_bf16 v[42:45], v[122:125], v[218:221], v[42:45]
	v_mfma_f32_16x16x32_bf16 v[30:33], v[114:117], v[226:229], v[30:33]
	v_mfma_f32_16x16x32_bf16 v[26:29], v[122:125], v[226:229], v[26:29]
	v_mfma_f32_16x16x32_bf16 v[14:17], v[114:117], v[234:237], v[14:17]
	v_mfma_f32_16x16x32_bf16 v[10:13], v[122:125], v[234:237], v[10:13]
	v_mfma_f32_16x16x32_bf16 v[62:65], v[118:121], v[200:203], v[62:65]
	v_mfma_f32_16x16x32_bf16 v[58:61], v[134:137], v[200:203], v[58:61]
	v_mfma_f32_16x16x32_bf16 v[46:49], v[118:121], v[222:225], v[46:49]
	v_mfma_f32_16x16x32_bf16 v[42:45], v[134:137], v[222:225], v[42:45]
	v_mfma_f32_16x16x32_bf16 v[30:33], v[118:121], v[230:233], v[30:33]
	v_mfma_f32_16x16x32_bf16 v[26:29], v[134:137], v[230:233], v[26:29]
	v_mfma_f32_16x16x32_bf16 v[14:17], v[118:121], v[238:241], v[14:17]
	v_mfma_f32_16x16x32_bf16 v[10:13], v[134:137], v[238:241], v[10:13]
	v_mfma_f32_16x16x32_bf16 v[54:57], v[146:149], v[196:199], v[54:57]
	v_mfma_f32_16x16x32_bf16 v[50:53], v[180:183], v[196:199], v[50:53]
	v_mfma_f32_16x16x32_bf16 v[38:41], v[146:149], v[218:221], v[38:41]
	v_mfma_f32_16x16x32_bf16 v[34:37], v[180:183], v[218:221], v[34:37]
	v_mfma_f32_16x16x32_bf16 v[22:25], v[146:149], v[226:229], v[22:25]
	v_mfma_f32_16x16x32_bf16 v[18:21], v[180:183], v[226:229], v[18:21]
	v_mfma_f32_16x16x32_bf16 v[6:9], v[146:149], v[234:237], v[6:9]
	v_mfma_f32_16x16x32_bf16 v[2:5], v[180:183], v[234:237], v[2:5]
	v_mfma_f32_16x16x32_bf16 v[54:57], v[150:153], v[200:203], v[54:57]
	v_mfma_f32_16x16x32_bf16 v[50:53], v[184:187], v[200:203], v[50:53]
	v_mfma_f32_16x16x32_bf16 v[38:41], v[150:153], v[222:225], v[38:41]
	v_mfma_f32_16x16x32_bf16 v[34:37], v[184:187], v[222:225], v[34:37]
	v_mfma_f32_16x16x32_bf16 v[22:25], v[150:153], v[230:233], v[22:25]
	v_mfma_f32_16x16x32_bf16 v[18:21], v[184:187], v[230:233], v[18:21]
	v_mfma_f32_16x16x32_bf16 v[6:9], v[150:153], v[238:241], v[6:9]
	v_mfma_f32_16x16x32_bf16 v[2:5], v[184:187], v[238:241], v[2:5]
	s_barrier
	s_add_i32 vcc_hi, vcc_hi, 2
	s_add_u32 s16, s16, 0x100
	s_addc_u32 s17, s17, 0
	s_add_u32 s78, s78, 0x100
	s_addc_u32 vcc_lo, vcc_lo, 0
	s_cmp_gt_u32 vcc_hi, 29
	s_cbranch_scc0 .LBB0_553
	s_and_b64 vcc, exec, s[6:7]
	s_cbranch_vccz .LBB0_556
	s_barrier

; #define PG8_STAGE(bufoff, gbase, voff) do { _Pragma("unroll") for (int _i = 0; _i < 2; ++_i) \
;         __builtin_amdgcn_global_load_lds((const unsigned*)((const char*)(gbase) + (voff)[_i]), (PG8_LAS unsigned*)(lds + (bufoff) + ldsw + _i * 8192), 16, 0, 0); } while (0)
; #define PG8_LDA(dst, b, h) do { _Pragma("unroll") for (int m = 0; m < 4; ++m) _Pragma("unroll") for (int k = 0; k < 2; ++k) dst[m][k] = *(const PG8_LAS bf16x8*)(lds + PG8_SA(b, h) + aoff + m * 2048 + k * 1024); } while (0)
; #define PG8_LDB(dst, b, h) do { _Pragma("unroll") for (int n = 0; n < 2; ++n) _Pragma("unroll") for (int k = 0; k < 2; ++k) dst[n][k] = *(const PG8_LAS bf16x8*)(lds + PG8_SB(b, h) + boff + n * 2048 + k * 1024); } while (0)
; #define PG8_MMA(ai, bj, At, Bt) do { __builtin_amdgcn_s_setprio(1); _Pragma("unroll") for (int m = 0; m < 4; ++m) _Pragma("unroll") for (int n = 0; n < 2; ++n) _Pragma("unroll") for (int k = 0; k < 2; ++k) \
;         acc[ai][bj][m][n] = __builtin_amdgcn_mfma_f32_16x16x32_bf16(Bt[n][k], At[m][k], acc[ai][bj][m][n], 0, 0, 0); __builtin_amdgcn_s_setprio(0); } while (0)
; #define PG8_WAIT_V(n) asm volatile("s_waitcnt vmcnt(" #n ")" ::: "memory")
; #define PG8_WAIT_L(n) asm volatile("s_waitcnt lgkmcnt(" #n ")" ::: "memory")
; template <class Epi, class Sched, bool ALIGN_EPI = false, bool SP2 = false>
; __device__ __forceinline__ void gemm_phase(PG8_LAS unsigned char* lds, const Gemm g, const Sched& S, const Epi& E) {
;     ...
;             const bool last = (t == nt - 2);
;             const char* a1 = cA + (size_t)(t + 1) * kstep;
;             const char* a2 = last ? nA : cA + (size_t)(t + 2) * kstep; const char* b2 = last ? nB : cB + (size_t)(t + 2) * kstep;
;             const char* a3 = a2 + kstep; const char* b3 = b2 + kstep;
;             if (last && has_next) S.a_ready(nxt);
;             if constexpr (SP2) {
;             PG8_LDB(B0, 0, 0); PG8_LDB(B1, 0, 1); PG8_SCHED; PG8_LDA(At, 0, 0); PG8_STAGE(PG8_SA(1, 1), a1 + hstep, voffA);
;             PG8_WAIT_V(8); PG8_WAIT_L(0); PG8_BAR; PG8_MMA(0, 0, At, B0); PG8_MMA(0, 1, At, B1); PG8_BAR; PG8_SCHED;
;             PG8_LDA(At, 0, 1); PG8_STAGE(PG8_SB(0, 0), b2, voffB); PG8_STAGE(PG8_SB(0, 1), b2 + hstep, voffB); PG8_STAGE(PG8_SA(0, 0), a2, voffA);
;             PG8_WAIT_V(8); PG8_WAIT_L(0); PG8_BAR; PG8_MMA(1, 0, At, B0); PG8_MMA(1, 1, At, B1); PG8_BAR; PG8_SCHED;
.LBB0_659:
	s_add_u32 s26, s16, 0xfff80080
	s_addc_u32 s27, s17, -1
	s_add_i32 s54, 0, 0x10000
	s_cmp_eq_u32 s77, 28
	s_cselect_b32 s29, s23, s27
	s_cselect_b32 s28, s43, s26
	s_cselect_b32 s27, s21, s73
	s_cselect_b32 s26, s52, s53
	s_add_i32 s78, 0, 0x14000
	v_add_u32_e32 v154, s54, v159
	v_add_u32_e32 v163, s78, v159
	ds_read_b128 v[142:145], v154
	ds_read_b128 v[146:149], v154 offset:1024
	ds_read_b128 v[150:153], v154 offset:2048
	ds_read_b128 v[154:157], v154 offset:3072
	ds_read_b128 v[164:167], v163
	ds_read_b128 v[180:183], v163 offset:1024
	ds_read_b128 v[184:187], v163 offset:2048
	ds_read_b128 v[188:191], v163 offset:3072
	s_add_i32 m0, s45, 0xc000
	ds_read_b128 v[192:195], v162
	ds_read_b128 v[196:199], v162 offset:1024
	ds_read_b128 v[200:203], v162 offset:2048
	ds_read_b128 v[218:221], v162 offset:3072
	ds_read_b128 v[222:225], v162 offset:4096
	ds_read_b128 v[226:229], v162 offset:5120
	ds_read_b128 v[230:233], v162 offset:6144
	ds_read_b128 v[234:237], v162 offset:7168
	global_load_lds_dwordx4 v138, s[16:17]
	s_add_i32 m0, s45, 0xe000
	s_nop 0
	global_load_lds_dwordx4 v140, s[16:17]
	s_waitcnt vmcnt(8)
	s_waitcnt lgkmcnt(0)
	s_barrier
	v_mfma_f32_16x16x32_bf16 v[126:129], v[142:145], v[192:195], v[126:129]
	v_mfma_f32_16x16x32_bf16 v[118:121], v[150:153], v[192:195], v[118:121]
	v_mfma_f32_16x16x32_bf16 v[110:113], v[142:145], v[200:203], v[110:113]
	v_mfma_f32_16x16x32_bf16 v[102:105], v[150:153], v[200:203], v[102:105]
	v_mfma_f32_16x16x32_bf16 v[94:97], v[142:145], v[222:225], v[94:97]
	v_mfma_f32_16x16x32_bf16 v[86:89], v[150:153], v[222:225], v[86:89]
	v_mfma_f32_16x16x32_bf16 v[78:81], v[142:145], v[230:233], v[78:81]
	v_mfma_f32_16x16x32_bf16 v[70:73], v[150:153], v[230:233], v[70:73]
	v_mfma_f32_16x16x32_bf16 v[126:129], v[146:149], v[196:199], v[126:129]
	v_mfma_f32_16x16x32_bf16 v[118:121], v[154:157], v[196:199], v[118:121]
	v_mfma_f32_16x16x32_bf16 v[110:113], v[146:149], v[218:221], v[110:113]
	v_mfma_f32_16x16x32_bf16 v[102:105], v[154:157], v[218:221], v[102:105]
	v_mfma_f32_16x16x32_bf16 v[94:97], v[146:149], v[226:229], v[94:97]
	v_mfma_f32_16x16x32_bf16 v[86:89], v[154:157], v[226:229], v[86:89]
	v_mfma_f32_16x16x32_bf16 v[78:81], v[146:149], v[234:237], v[78:81]
	v_mfma_f32_16x16x32_bf16 v[70:73], v[154:157], v[234:237], v[70:73]
	v_mfma_f32_16x16x32_bf16 v[122:125], v[164:167], v[192:195], v[122:125]
	v_mfma_f32_16x16x32_bf16 v[114:117], v[184:187], v[192:195], v[114:117]
	v_mfma_f32_16x16x32_bf16 v[106:109], v[164:167], v[200:203], v[106:109]
	v_mfma_f32_16x16x32_bf16 v[98:101], v[184:187], v[200:203], v[98:101]
	v_mfma_f32_16x16x32_bf16 v[90:93], v[164:167], v[222:225], v[90:93]
	v_mfma_f32_16x16x32_bf16 v[82:85], v[184:187], v[222:225], v[82:85]
	v_mfma_f32_16x16x32_bf16 v[74:77], v[164:167], v[230:233], v[74:77]
	v_mfma_f32_16x16x32_bf16 v[66:69], v[184:187], v[230:233], v[66:69]
	v_mfma_f32_16x16x32_bf16 v[122:125], v[180:183], v[196:199], v[122:125]
	v_mfma_f32_16x16x32_bf16 v[114:117], v[188:191], v[196:199], v[114:117]
	v_mfma_f32_16x16x32_bf16 v[106:109], v[180:183], v[218:221], v[106:109]
	v_mfma_f32_16x16x32_bf16 v[98:101], v[188:191], v[218:221], v[98:101]
	v_mfma_f32_16x16x32_bf16 v[90:93], v[180:183], v[226:229], v[90:93]
	v_mfma_f32_16x16x32_bf16 v[82:85], v[188:191], v[226:229], v[82:85]
	v_mfma_f32_16x16x32_bf16 v[74:77], v[180:183], v[234:237], v[74:77]
	v_mfma_f32_16x16x32_bf16 v[66:69], v[188:191], v[234:237], v[66:69]
	s_barrier
	s_add_i32 s54, s54, s38
	s_mov_b32 m0, s54
	ds_read_b128 v[192:195], v162 offset:16384
	ds_read_b128 v[196:199], v162 offset:17408
	ds_read_b128 v[200:203], v162 offset:18432
	ds_read_b128 v[218:221], v162 offset:19456
	ds_read_b128 v[222:225], v162 offset:20480
	ds_read_b128 v[226:229], v162 offset:21504
	ds_read_b128 v[230:233], v162 offset:22528
	ds_read_b128 v[234:237], v162 offset:23552
	global_load_lds_dwordx4 v0, s[26:27]
	s_add_i32 m0, s54, 0x2000
	s_add_u32 s54, s26, 0x80000
	v_lshl_add_u64 v[240:241], s[26:27], 0, v[130:131]
	s_addc_u32 s55, s27, 0
	s_add_i32 s78, s78, s38
	global_load_lds_dwordx4 v130, s[26:27]
	s_mov_b32 m0, s78
	v_lshl_add_u64 v[244:245], s[28:29], 0, v[132:133]
	global_load_lds_dwordx4 v0, s[54:55]
	s_add_i32 m0, s78, 0x2000
	s_nop 0
	global_load_lds_dwordx4 v130, s[54:55]
	v_lshl_add_u64 v[242:243], s[28:29], 0, v[134:135]
	s_mov_b32 m0, s45
	s_nop 0
	global_load_lds_dwordx4 v134, s[28:29]
	s_mov_b32 m0, s46
	s_nop 0
	global_load_lds_dwordx4 v132, s[28:29]
	s_waitcnt vmcnt(8)
	s_waitcnt lgkmcnt(0)
	s_barrier
	v_mfma_f32_16x16x32_bf16 v[62:65], v[142:145], v[192:195], v[62:65]
	v_mfma_f32_16x16x32_bf16 v[54:57], v[150:153], v[192:195], v[54:57]
	v_mfma_f32_16x16x32_bf16 v[46:49], v[142:145], v[200:203], v[46:49]
	v_mfma_f32_16x16x32_bf16 v[38:41], v[150:153], v[200:203], v[38:41]
	v_mfma_f32_16x16x32_bf16 v[30:33], v[142:145], v[222:225], v[30:33]
	v_mfma_f32_16x16x32_bf16 v[22:25], v[150:153], v[222:225], v[22:25]
	v_mfma_f32_16x16x32_bf16 v[14:17], v[142:145], v[230:233], v[14:17]
	v_mfma_f32_16x16x32_bf16 v[6:9], v[150:153], v[230:233], v[6:9]
	v_mfma_f32_16x16x32_bf16 v[62:65], v[146:149], v[196:199], v[62:65]
	v_mfma_f32_16x16x32_bf16 v[54:57], v[154:157], v[196:199], v[54:57]
	v_mfma_f32_16x16x32_bf16 v[46:49], v[146:149], v[218:221], v[46:49]
	v_mfma_f32_16x16x32_bf16 v[38:41], v[154:157], v[218:221], v[38:41]
	v_mfma_f32_16x16x32_bf16 v[30:33], v[146:149], v[226:229], v[30:33]
	v_mfma_f32_16x16x32_bf16 v[22:25], v[154:157], v[226:229], v[22:25]
	v_mfma_f32_16x16x32_bf16 v[14:17], v[146:149], v[234:237], v[14:17]
	v_mfma_f32_16x16x32_bf16 v[6:9], v[154:157], v[234:237], v[6:9]
	v_mfma_f32_16x16x32_bf16 v[58:61], v[164:167], v[192:195], v[58:61]
	v_mfma_f32_16x16x32_bf16 v[50:53], v[184:187], v[192:195], v[50:53]
	v_mfma_f32_16x16x32_bf16 v[42:45], v[164:167], v[200:203], v[42:45]
	v_mfma_f32_16x16x32_bf16 v[34:37], v[184:187], v[200:203], v[34:37]
	v_mfma_f32_16x16x32_bf16 v[26:29], v[164:167], v[222:225], v[26:29]
	v_mfma_f32_16x16x32_bf16 v[18:21], v[184:187], v[222:225], v[18:21]
	v_mfma_f32_16x16x32_bf16 v[10:13], v[164:167], v[230:233], v[10:13]
	v_mfma_f32_16x16x32_bf16 v[2:5], v[184:187], v[230:233], v[2:5]
	v_mfma_f32_16x16x32_bf16 v[58:61], v[180:183], v[196:199], v[58:61]
	v_mfma_f32_16x16x32_bf16 v[50:53], v[188:191], v[196:199], v[50:53]
	v_mfma_f32_16x16x32_bf16 v[42:45], v[180:183], v[218:221], v[42:45]
	v_mfma_f32_16x16x32_bf16 v[34:37], v[188:191], v[218:221], v[34:37]
	v_mfma_f32_16x16x32_bf16 v[26:29], v[180:183], v[226:229], v[26:29]
	v_mfma_f32_16x16x32_bf16 v[18:21], v[188:191], v[226:229], v[18:21]
	v_mfma_f32_16x16x32_bf16 v[10:13], v[180:183], v[234:237], v[10:13]
	v_mfma_f32_16x16x32_bf16 v[2:5], v[188:191], v[234:237], v[2:5]
	s_barrier
; #define PG8_STAGE(bufoff, gbase, voff) do { _Pragma("unroll") for (int _i = 0; _i < 2; ++_i) \
;         __builtin_amdgcn_global_load_lds((const unsigned*)((const char*)(gbase) + (voff)[_i]), (PG8_LAS unsigned*)(lds + (bufoff) + ldsw + _i * 8192), 16, 0, 0); } while (0)
; #define PG8_LDA(dst, b, h) do { _Pragma("unroll") for (int m = 0; m < 4; ++m) _Pragma("unroll") for (int k = 0; k < 2; ++k) dst[m][k] = *(const PG8_LAS bf16x8*)(lds + PG8_SA(b, h) + aoff + m * 2048 + k * 1024); } while (0)
; #define PG8_LDB(dst, b, h) do { _Pragma("unroll") for (int n = 0; n < 2; ++n) _Pragma("unroll") for (int k = 0; k < 2; ++k) dst[n][k] = *(const PG8_LAS bf16x8*)(lds + PG8_SB(b, h) + boff + n * 2048 + k * 1024); } while (0)
; #define PG8_MMA(ai, bj, At, Bt) do { __builtin_amdgcn_s_setprio(1); _Pragma("unroll") for (int m = 0; m < 4; ++m) _Pragma("unroll") for (int n = 0; n < 2; ++n) _Pragma("unroll") for (int k = 0; k < 2; ++k) \
;         acc[ai][bj][m][n] = __builtin_amdgcn_mfma_f32_16x16x32_bf16(Bt[n][k], At[m][k], acc[ai][bj][m][n], 0, 0, 0); __builtin_amdgcn_s_setprio(0); } while (0)
; #define PG8_WAIT_V(n) asm volatile("s_waitcnt vmcnt(" #n ")" ::: "memory")
; #define PG8_WAIT_L(n) asm volatile("s_waitcnt lgkmcnt(" #n ")" ::: "memory")
; #define PG8_BAR __builtin_amdgcn_s_barrier()
; #define PG8_SCHED __builtin_amdgcn_sched_barrier(0)
; template <class Epi, class Sched, bool ALIGN_EPI = false, bool SP2 = false>
; __device__ __forceinline__ void gemm_phase(PG8_LAS unsigned char* lds, const Gemm g, const Sched& S, const Epi& E) {
;     ...
;             PG8_LDB(B0, 1, 0); PG8_LDB(B1, 1, 1); PG8_SCHED; PG8_LDA(At, 1, 0); PG8_STAGE(PG8_SA(0, 1), a2 + hstep, voffA);
;             PG8_WAIT_V(8); PG8_WAIT_L(0); PG8_BAR; PG8_MMA(0, 0, At, B0); PG8_MMA(0, 1, At, B1); PG8_BAR; PG8_SCHED;
;             PG8_LDA(At, 1, 1); PG8_STAGE(PG8_SB(1, 0), b3, voffB); PG8_STAGE(PG8_SB(1, 1), b3 + hstep, voffB); PG8_STAGE(PG8_SA(1, 0), a3, voffA);
;             PG8_WAIT_V(8); PG8_WAIT_L(0); PG8_BAR; PG8_MMA(1, 0, At, B0); PG8_MMA(1, 1, At, B1); PG8_BAR; PG8_SCHED;
;     ...
;         if constexpr (ALIGN_EPI) { if (wr == 0) PG8_BAR; }
	s_add_i32 s54, 0, 0x18000
	s_add_i32 s55, 0, 0x1c000
	v_add_u32_e32 v154, s54, v159
	v_add_u32_e32 v163, s55, v159
	ds_read_b128 v[142:145], v154
	ds_read_b128 v[146:149], v154 offset:1024
	ds_read_b128 v[150:153], v154 offset:2048
	ds_read_b128 v[154:157], v154 offset:3072
	ds_read_b128 v[164:167], v163
	ds_read_b128 v[180:183], v163 offset:1024
	ds_read_b128 v[184:187], v163 offset:2048
	ds_read_b128 v[188:191], v163 offset:3072
	s_add_u32 s28, s28, 0x80000
	s_addc_u32 s29, s29, 0
	s_mov_b32 m0, s47
	ds_read_b128 v[192:195], v162 offset:32768
	ds_read_b128 v[196:199], v162 offset:33792
	ds_read_b128 v[200:203], v162 offset:34816
	ds_read_b128 v[218:221], v162 offset:35840
	ds_read_b128 v[222:225], v162 offset:36864
	ds_read_b128 v[226:229], v162 offset:37888
	ds_read_b128 v[230:233], v162 offset:38912
	ds_read_b128 v[234:237], v162 offset:39936
	global_load_lds_dwordx4 v134, s[28:29]
	s_mov_b32 m0, s48
	s_nop 0
	global_load_lds_dwordx4 v132, s[28:29]
	s_waitcnt vmcnt(8)
	s_waitcnt lgkmcnt(0)
	s_barrier
	v_mfma_f32_16x16x32_bf16 v[126:129], v[142:145], v[192:195], v[126:129]
	v_mfma_f32_16x16x32_bf16 v[118:121], v[150:153], v[192:195], v[118:121]
	v_mfma_f32_16x16x32_bf16 v[110:113], v[142:145], v[200:203], v[110:113]
	v_mfma_f32_16x16x32_bf16 v[102:105], v[150:153], v[200:203], v[102:105]
	v_mfma_f32_16x16x32_bf16 v[94:97], v[142:145], v[222:225], v[94:97]
	v_mfma_f32_16x16x32_bf16 v[86:89], v[150:153], v[222:225], v[86:89]
	v_mfma_f32_16x16x32_bf16 v[78:81], v[142:145], v[230:233], v[78:81]
	v_mfma_f32_16x16x32_bf16 v[70:73], v[150:153], v[230:233], v[70:73]
	v_mfma_f32_16x16x32_bf16 v[126:129], v[146:149], v[196:199], v[126:129]
	v_mfma_f32_16x16x32_bf16 v[118:121], v[154:157], v[196:199], v[118:121]
	v_mfma_f32_16x16x32_bf16 v[110:113], v[146:149], v[218:221], v[110:113]
	v_mfma_f32_16x16x32_bf16 v[102:105], v[154:157], v[218:221], v[102:105]
	v_mfma_f32_16x16x32_bf16 v[94:97], v[146:149], v[226:229], v[94:97]
	v_mfma_f32_16x16x32_bf16 v[86:89], v[154:157], v[226:229], v[86:89]
	v_mfma_f32_16x16x32_bf16 v[78:81], v[146:149], v[234:237], v[78:81]
	v_mfma_f32_16x16x32_bf16 v[70:73], v[154:157], v[234:237], v[70:73]
	v_mfma_f32_16x16x32_bf16 v[122:125], v[164:167], v[192:195], v[122:125]
	v_mfma_f32_16x16x32_bf16 v[114:117], v[184:187], v[192:195], v[114:117]
	v_mfma_f32_16x16x32_bf16 v[106:109], v[164:167], v[200:203], v[106:109]
	v_mfma_f32_16x16x32_bf16 v[98:101], v[184:187], v[200:203], v[98:101]
	v_mfma_f32_16x16x32_bf16 v[90:93], v[164:167], v[222:225], v[90:93]
	v_mfma_f32_16x16x32_bf16 v[82:85], v[184:187], v[222:225], v[82:85]
	v_mfma_f32_16x16x32_bf16 v[74:77], v[164:167], v[230:233], v[74:77]
	v_mfma_f32_16x16x32_bf16 v[66:69], v[184:187], v[230:233], v[66:69]
	v_mfma_f32_16x16x32_bf16 v[122:125], v[180:183], v[196:199], v[122:125]
	v_mfma_f32_16x16x32_bf16 v[114:117], v[188:191], v[196:199], v[114:117]
	v_mfma_f32_16x16x32_bf16 v[106:109], v[180:183], v[218:221], v[106:109]
	v_mfma_f32_16x16x32_bf16 v[98:101], v[188:191], v[218:221], v[98:101]
	v_mfma_f32_16x16x32_bf16 v[90:93], v[180:183], v[226:229], v[90:93]
	v_mfma_f32_16x16x32_bf16 v[82:85], v[188:191], v[226:229], v[82:85]
	v_mfma_f32_16x16x32_bf16 v[74:77], v[180:183], v[234:237], v[74:77]
	v_mfma_f32_16x16x32_bf16 v[66:69], v[188:191], v[234:237], v[66:69]
	s_barrier
	s_add_i32 s28, s54, s38
	s_add_i32 m0, s28, 0xffffff80
	ds_read_b128 v[192:195], v162 offset:49152
	ds_read_b128 v[196:199], v162 offset:50176
	ds_read_b128 v[200:203], v162 offset:51200
	ds_read_b128 v[218:221], v162 offset:52224
	ds_read_b128 v[222:225], v162 offset:53248
	ds_read_b128 v[226:229], v162 offset:54272
	ds_read_b128 v[230:233], v162 offset:55296
	ds_read_b128 v[234:237], v162 offset:56320
	global_load_lds_dwordx4 v0, s[26:27] offset:128
	s_add_i32 m0, s28, 0x2000
	s_add_u32 s26, s26, 0x80080
	v_lshl_add_u64 v[238:239], v[240:241], 0, s[34:35]
	s_addc_u32 s27, s27, 0
	s_add_i32 s28, s55, s38
	global_load_lds_dwordx4 v[238:239], off
	s_mov_b32 m0, s28
	s_nop 0
	global_load_lds_dwordx4 v0, s[26:27]
	s_add_i32 m0, s28, 0x2000
	s_nop 0
	global_load_lds_dwordx4 v130, s[26:27]
	v_lshl_add_u64 v[238:239], v[242:243], 0, s[34:35]
	s_mov_b32 m0, s4
	s_nop 0
	global_load_lds_dwordx4 v[238:239], off
	v_lshl_add_u64 v[238:239], v[244:245], 0, s[34:35]
	s_mov_b32 m0, s49
	s_nop 0
	global_load_lds_dwordx4 v[238:239], off
	s_waitcnt vmcnt(8)
	s_waitcnt lgkmcnt(0)
	s_barrier
	v_mfma_f32_16x16x32_bf16 v[62:65], v[142:145], v[192:195], v[62:65]
	v_mfma_f32_16x16x32_bf16 v[54:57], v[150:153], v[192:195], v[54:57]
	v_mfma_f32_16x16x32_bf16 v[46:49], v[142:145], v[200:203], v[46:49]
	v_mfma_f32_16x16x32_bf16 v[38:41], v[150:153], v[200:203], v[38:41]
	v_mfma_f32_16x16x32_bf16 v[30:33], v[142:145], v[222:225], v[30:33]
	v_mfma_f32_16x16x32_bf16 v[22:25], v[150:153], v[222:225], v[22:25]
	v_mfma_f32_16x16x32_bf16 v[14:17], v[142:145], v[230:233], v[14:17]
	v_mfma_f32_16x16x32_bf16 v[6:9], v[150:153], v[230:233], v[6:9]
	v_mfma_f32_16x16x32_bf16 v[62:65], v[146:149], v[196:199], v[62:65]
	v_mfma_f32_16x16x32_bf16 v[54:57], v[154:157], v[196:199], v[54:57]
	v_mfma_f32_16x16x32_bf16 v[46:49], v[146:149], v[218:221], v[46:49]
	v_mfma_f32_16x16x32_bf16 v[38:41], v[154:157], v[218:221], v[38:41]
	v_mfma_f32_16x16x32_bf16 v[30:33], v[146:149], v[226:229], v[30:33]
	v_mfma_f32_16x16x32_bf16 v[22:25], v[154:157], v[226:229], v[22:25]
	v_mfma_f32_16x16x32_bf16 v[14:17], v[146:149], v[234:237], v[14:17]
	v_mfma_f32_16x16x32_bf16 v[6:9], v[154:157], v[234:237], v[6:9]
	v_mfma_f32_16x16x32_bf16 v[58:61], v[164:167], v[192:195], v[58:61]
	v_mfma_f32_16x16x32_bf16 v[50:53], v[184:187], v[192:195], v[50:53]
	v_mfma_f32_16x16x32_bf16 v[42:45], v[164:167], v[200:203], v[42:45]
	v_mfma_f32_16x16x32_bf16 v[34:37], v[184:187], v[200:203], v[34:37]
	v_mfma_f32_16x16x32_bf16 v[26:29], v[164:167], v[222:225], v[26:29]
	v_mfma_f32_16x16x32_bf16 v[18:21], v[184:187], v[222:225], v[18:21]
	v_mfma_f32_16x16x32_bf16 v[10:13], v[164:167], v[230:233], v[10:13]
	v_mfma_f32_16x16x32_bf16 v[2:5], v[184:187], v[230:233], v[2:5]
	v_mfma_f32_16x16x32_bf16 v[58:61], v[180:183], v[196:199], v[58:61]
	v_mfma_f32_16x16x32_bf16 v[50:53], v[188:191], v[196:199], v[50:53]
	v_mfma_f32_16x16x32_bf16 v[42:45], v[180:183], v[218:221], v[42:45]
	v_mfma_f32_16x16x32_bf16 v[34:37], v[188:191], v[218:221], v[34:37]
	v_mfma_f32_16x16x32_bf16 v[26:29], v[180:183], v[226:229], v[26:29]
	v_mfma_f32_16x16x32_bf16 v[18:21], v[188:191], v[226:229], v[18:21]
	v_mfma_f32_16x16x32_bf16 v[10:13], v[180:183], v[234:237], v[10:13]
	v_mfma_f32_16x16x32_bf16 v[2:5], v[188:191], v[234:237], v[2:5]
	s_barrier
	s_add_i32 s77, s77, 2
	s_add_u32 s16, s16, 0x100
	s_addc_u32 s17, s17, 0
	s_add_u32 s53, s53, 0x100
	s_addc_u32 s73, s73, 0
	s_cmp_gt_u32 s77, 29
	s_cbranch_scc0 .LBB0_659
	s_and_b64 vcc, exec, s[18:19]
	s_cbranch_vccz .LBB0_662
	s_barrier

; #define PG8_STAGE(bufoff, gbase, voff) do { _Pragma("unroll") for (int _i = 0; _i < 2; ++_i) \
;         __builtin_amdgcn_global_load_lds((const unsigned*)((const char*)(gbase) + (voff)[_i]), (PG8_LAS unsigned*)(lds + (bufoff) + ldsw + _i * 8192), 16, 0, 0); } while (0)
; #define PG8_LDA(dst, b, h) do { _Pragma("unroll") for (int m = 0; m < 4; ++m) _Pragma("unroll") for (int k = 0; k < 2; ++k) dst[m][k] = *(const PG8_LAS bf16x8*)(lds + PG8_SA(b, h) + aoff + m * 2048 + k * 1024); } while (0)
; #define PG8_LDB(dst, b, h) do { _Pragma("unroll") for (int n = 0; n < 2; ++n) _Pragma("unroll") for (int k = 0; k < 2; ++k) dst[n][k] = *(const PG8_LAS bf16x8*)(lds + PG8_SB(b, h) + boff + n * 2048 + k * 1024); } while (0)
; #define PG8_MMA(ai, bj, At, Bt) do { __builtin_amdgcn_s_setprio(1); _Pragma("unroll") for (int m = 0; m < 4; ++m) _Pragma("unroll") for (int n = 0; n < 2; ++n) _Pragma("unroll") for (int k = 0; k < 2; ++k) \
;         acc[ai][bj][m][n] = __builtin_amdgcn_mfma_f32_16x16x32_bf16(Bt[n][k], At[m][k], acc[ai][bj][m][n], 0, 0, 0); __builtin_amdgcn_s_setprio(0); } while (0)
; #define PG8_WAIT_V(n) asm volatile("s_waitcnt vmcnt(" #n ")" ::: "memory")
; #define PG8_WAIT_L(n) asm volatile("s_waitcnt lgkmcnt(" #n ")" ::: "memory")
; template <class Epi, class Sched, bool ALIGN_EPI = false, bool SP2 = false>
; __device__ __forceinline__ void gemm_phase(PG8_LAS unsigned char* lds, const Gemm g, const Sched& S, const Epi& E) {
;     ...
;             const bool last = (t == nt - 2);
;             const char* a1 = cA + (size_t)(t + 1) * kstep;
;             const char* a2 = last ? nA : cA + (size_t)(t + 2) * kstep; const char* b2 = last ? nB : cB + (size_t)(t + 2) * kstep;
;             const char* a3 = a2 + kstep; const char* b3 = b2 + kstep;
;             if (last && has_next) S.a_ready(nxt);
;             if constexpr (SP2) {
;             PG8_LDB(B0, 0, 0); PG8_LDB(B1, 0, 1); PG8_SCHED; PG8_LDA(At, 0, 0); PG8_STAGE(PG8_SA(1, 1), a1 + hstep, voffA);
;             PG8_WAIT_V(8); PG8_WAIT_L(0); PG8_BAR; PG8_MMA(0, 0, At, B0); PG8_MMA(0, 1, At, B1); PG8_BAR; PG8_SCHED;
;             PG8_LDA(At, 0, 1); PG8_STAGE(PG8_SB(0, 0), b2, voffB); PG8_STAGE(PG8_SB(0, 1), b2 + hstep, voffB); PG8_STAGE(PG8_SA(0, 0), a2, voffA);
;             PG8_WAIT_V(8); PG8_WAIT_L(0); PG8_BAR; PG8_MMA(1, 0, At, B0); PG8_MMA(1, 1, At, B1); PG8_BAR; PG8_SCHED;
.LBB0_802:
	s_add_u32 s24, s22, 0x100
	s_addc_u32 s25, s23, 0
	s_add_i32 s54, 0, 0x10000
	s_cmpk_eq_i32 s78, 0x54
	s_cselect_b32 s29, s19, s25
	s_cselect_b32 s28, s18, s24
	s_cselect_b32 s27, s21, s45
	s_cselect_b32 s26, s20, s44
	s_add_i32 s55, 0, 0x14000
	v_add_u32_e32 v142, s54, v199
	v_add_u32_e32 v182, s55, v199
	ds_read_b128 v[122:125], v142
	ds_read_b128 v[134:137], v142 offset:1024
	ds_read_b128 v[138:141], v142 offset:2048
	ds_read_b128 v[142:145], v142 offset:3072
	ds_read_b128 v[146:149], v182
	ds_read_b128 v[150:153], v182 offset:1024
	ds_read_b128 v[154:157], v182 offset:2048
	ds_read_b128 v[182:185], v182 offset:3072
	s_add_i32 m0, s46, 0xc000
	ds_read_b128 v[186:189], v202
	ds_read_b128 v[190:193], v202 offset:1024
	ds_read_b128 v[194:197], v202 offset:2048
	ds_read_b128 v[218:221], v202 offset:3072
	ds_read_b128 v[222:225], v202 offset:4096
	ds_read_b128 v[226:229], v202 offset:5120
	ds_read_b128 v[230:233], v202 offset:6144
	ds_read_b128 v[234:237], v202 offset:7168
	global_load_lds_dwordx4 v166, s[22:23]
	s_add_i32 m0, s46, 0xe000
	s_nop 0
	global_load_lds_dwordx4 v180, s[22:23]
	s_waitcnt vmcnt(8)
	s_waitcnt lgkmcnt(0)
	s_barrier
	v_mfma_f32_16x16x32_bf16 v[130:133], v[122:125], v[186:189], v[130:133]
	v_mfma_f32_16x16x32_bf16 v[126:129], v[138:141], v[186:189], v[126:129]
	v_mfma_f32_16x16x32_bf16 v[110:113], v[122:125], v[194:197], v[110:113]
	v_mfma_f32_16x16x32_bf16 v[106:109], v[138:141], v[194:197], v[106:109]
	v_mfma_f32_16x16x32_bf16 v[94:97], v[122:125], v[222:225], v[94:97]
	v_mfma_f32_16x16x32_bf16 v[90:93], v[138:141], v[222:225], v[90:93]
	v_mfma_f32_16x16x32_bf16 v[78:81], v[122:125], v[230:233], v[78:81]
	v_mfma_f32_16x16x32_bf16 v[74:77], v[138:141], v[230:233], v[74:77]
	v_mfma_f32_16x16x32_bf16 v[130:133], v[134:137], v[190:193], v[130:133]
	v_mfma_f32_16x16x32_bf16 v[126:129], v[142:145], v[190:193], v[126:129]
	v_mfma_f32_16x16x32_bf16 v[110:113], v[134:137], v[218:221], v[110:113]
	v_mfma_f32_16x16x32_bf16 v[106:109], v[142:145], v[218:221], v[106:109]
	v_mfma_f32_16x16x32_bf16 v[94:97], v[134:137], v[226:229], v[94:97]
	v_mfma_f32_16x16x32_bf16 v[90:93], v[142:145], v[226:229], v[90:93]
	v_mfma_f32_16x16x32_bf16 v[78:81], v[134:137], v[234:237], v[78:81]
	v_mfma_f32_16x16x32_bf16 v[74:77], v[142:145], v[234:237], v[74:77]
	v_mfma_f32_16x16x32_bf16 v[118:121], v[146:149], v[186:189], v[118:121]
	v_mfma_f32_16x16x32_bf16 v[114:117], v[154:157], v[186:189], v[114:117]
	v_mfma_f32_16x16x32_bf16 v[102:105], v[146:149], v[194:197], v[102:105]
	v_mfma_f32_16x16x32_bf16 v[98:101], v[154:157], v[194:197], v[98:101]
	v_mfma_f32_16x16x32_bf16 v[86:89], v[146:149], v[222:225], v[86:89]
	v_mfma_f32_16x16x32_bf16 v[82:85], v[154:157], v[222:225], v[82:85]
	v_mfma_f32_16x16x32_bf16 v[70:73], v[146:149], v[230:233], v[70:73]
	v_mfma_f32_16x16x32_bf16 v[66:69], v[154:157], v[230:233], v[66:69]
	v_mfma_f32_16x16x32_bf16 v[118:121], v[150:153], v[190:193], v[118:121]
	v_mfma_f32_16x16x32_bf16 v[114:117], v[182:185], v[190:193], v[114:117]
	v_mfma_f32_16x16x32_bf16 v[102:105], v[150:153], v[218:221], v[102:105]
	v_mfma_f32_16x16x32_bf16 v[98:101], v[182:185], v[218:221], v[98:101]
	v_mfma_f32_16x16x32_bf16 v[86:89], v[150:153], v[226:229], v[86:89]
	v_mfma_f32_16x16x32_bf16 v[82:85], v[182:185], v[226:229], v[82:85]
	v_mfma_f32_16x16x32_bf16 v[70:73], v[150:153], v[234:237], v[70:73]
	v_mfma_f32_16x16x32_bf16 v[66:69], v[182:185], v[234:237], v[66:69]
	s_barrier
	s_add_i32 s22, s54, s2
	s_mov_b32 m0, s22
	ds_read_b128 v[186:189], v202 offset:16384
	ds_read_b128 v[190:193], v202 offset:17408
	ds_read_b128 v[194:197], v202 offset:18432
	ds_read_b128 v[218:221], v202 offset:19456
	ds_read_b128 v[222:225], v202 offset:20480
	ds_read_b128 v[226:229], v202 offset:21504
	ds_read_b128 v[230:233], v202 offset:22528
	ds_read_b128 v[234:237], v202 offset:23552
	global_load_lds_dwordx4 v0, s[26:27]
	s_add_i32 m0, s22, 0x2000
	s_add_u32 s22, s26, 0x160000
	v_lshl_add_u64 v[240:241], s[26:27], 0, v[158:159]
	s_addc_u32 s23, s27, 0
	s_add_i32 s54, s55, s2
	global_load_lds_dwordx4 v158, s[26:27]
	s_mov_b32 m0, s54
	s_nop 0
	global_load_lds_dwordx4 v0, s[22:23]
	s_add_i32 m0, s54, 0x2000
	s_nop 0
	global_load_lds_dwordx4 v158, s[22:23]
	s_mov_b32 m0, s46
	s_nop 0
	global_load_lds_dwordx4 v162, s[28:29]
	s_mov_b32 m0, s47
	s_nop 0
	global_load_lds_dwordx4 v160, s[28:29]
	s_waitcnt vmcnt(8)
	s_waitcnt lgkmcnt(0)
	s_barrier
	v_mfma_f32_16x16x32_bf16 v[62:65], v[122:125], v[186:189], v[62:65]
	v_mfma_f32_16x16x32_bf16 v[58:61], v[138:141], v[186:189], v[58:61]
	v_mfma_f32_16x16x32_bf16 v[46:49], v[122:125], v[194:197], v[46:49]
	v_mfma_f32_16x16x32_bf16 v[42:45], v[138:141], v[194:197], v[42:45]
	v_mfma_f32_16x16x32_bf16 v[30:33], v[122:125], v[222:225], v[30:33]
	v_mfma_f32_16x16x32_bf16 v[26:29], v[138:141], v[222:225], v[26:29]
	v_mfma_f32_16x16x32_bf16 v[14:17], v[122:125], v[230:233], v[14:17]
	v_mfma_f32_16x16x32_bf16 v[10:13], v[138:141], v[230:233], v[10:13]
	v_mfma_f32_16x16x32_bf16 v[62:65], v[134:137], v[190:193], v[62:65]
	v_mfma_f32_16x16x32_bf16 v[58:61], v[142:145], v[190:193], v[58:61]
	v_mfma_f32_16x16x32_bf16 v[46:49], v[134:137], v[218:221], v[46:49]
	v_mfma_f32_16x16x32_bf16 v[42:45], v[142:145], v[218:221], v[42:45]
	v_mfma_f32_16x16x32_bf16 v[30:33], v[134:137], v[226:229], v[30:33]
	v_mfma_f32_16x16x32_bf16 v[26:29], v[142:145], v[226:229], v[26:29]
	v_mfma_f32_16x16x32_bf16 v[14:17], v[134:137], v[234:237], v[14:17]
	v_mfma_f32_16x16x32_bf16 v[10:13], v[142:145], v[234:237], v[10:13]
	v_mfma_f32_16x16x32_bf16 v[54:57], v[146:149], v[186:189], v[54:57]
	v_mfma_f32_16x16x32_bf16 v[50:53], v[154:157], v[186:189], v[50:53]
	v_mfma_f32_16x16x32_bf16 v[38:41], v[146:149], v[194:197], v[38:41]
	v_mfma_f32_16x16x32_bf16 v[34:37], v[154:157], v[194:197], v[34:37]
	v_mfma_f32_16x16x32_bf16 v[22:25], v[146:149], v[222:225], v[22:25]
	v_mfma_f32_16x16x32_bf16 v[18:21], v[154:157], v[222:225], v[18:21]
	v_mfma_f32_16x16x32_bf16 v[6:9], v[146:149], v[230:233], v[6:9]
	v_mfma_f32_16x16x32_bf16 v[2:5], v[154:157], v[230:233], v[2:5]
	v_mfma_f32_16x16x32_bf16 v[54:57], v[150:153], v[190:193], v[54:57]
	v_mfma_f32_16x16x32_bf16 v[50:53], v[182:185], v[190:193], v[50:53]
	v_mfma_f32_16x16x32_bf16 v[38:41], v[150:153], v[218:221], v[38:41]
	v_mfma_f32_16x16x32_bf16 v[34:37], v[182:185], v[218:221], v[34:37]
	v_mfma_f32_16x16x32_bf16 v[22:25], v[150:153], v[226:229], v[22:25]
	v_mfma_f32_16x16x32_bf16 v[18:21], v[182:185], v[226:229], v[18:21]
	v_mfma_f32_16x16x32_bf16 v[6:9], v[150:153], v[234:237], v[6:9]
	v_mfma_f32_16x16x32_bf16 v[2:5], v[182:185], v[234:237], v[2:5]
	s_barrier
; #define PG8_STAGE(bufoff, gbase, voff) do { _Pragma("unroll") for (int _i = 0; _i < 2; ++_i) \
;         __builtin_amdgcn_global_load_lds((const unsigned*)((const char*)(gbase) + (voff)[_i]), (PG8_LAS unsigned*)(lds + (bufoff) + ldsw + _i * 8192), 16, 0, 0); } while (0)
; #define PG8_LDA(dst, b, h) do { _Pragma("unroll") for (int m = 0; m < 4; ++m) _Pragma("unroll") for (int k = 0; k < 2; ++k) dst[m][k] = *(const PG8_LAS bf16x8*)(lds + PG8_SA(b, h) + aoff + m * 2048 + k * 1024); } while (0)
; #define PG8_LDB(dst, b, h) do { _Pragma("unroll") for (int n = 0; n < 2; ++n) _Pragma("unroll") for (int k = 0; k < 2; ++k) dst[n][k] = *(const PG8_LAS bf16x8*)(lds + PG8_SB(b, h) + boff + n * 2048 + k * 1024); } while (0)
; #define PG8_MMA(ai, bj, At, Bt) do { __builtin_amdgcn_s_setprio(1); _Pragma("unroll") for (int m = 0; m < 4; ++m) _Pragma("unroll") for (int n = 0; n < 2; ++n) _Pragma("unroll") for (int k = 0; k < 2; ++k) \
;         acc[ai][bj][m][n] = __builtin_amdgcn_mfma_f32_16x16x32_bf16(Bt[n][k], At[m][k], acc[ai][bj][m][n], 0, 0, 0); __builtin_amdgcn_s_setprio(0); } while (0)
; #define PG8_WAIT_V(n) asm volatile("s_waitcnt vmcnt(" #n ")" ::: "memory")
; #define PG8_WAIT_L(n) asm volatile("s_waitcnt lgkmcnt(" #n ")" ::: "memory")
; #define PG8_BAR __builtin_amdgcn_s_barrier()
; #define PG8_SCHED __builtin_amdgcn_sched_barrier(0)
; template <class Epi, class Sched, bool ALIGN_EPI = false, bool SP2 = false>
; __device__ __forceinline__ void gemm_phase(PG8_LAS unsigned char* lds, const Gemm g, const Sched& S, const Epi& E) {
;     ...
;             PG8_LDB(B0, 1, 0); PG8_LDB(B1, 1, 1); PG8_SCHED; PG8_LDA(At, 1, 0); PG8_STAGE(PG8_SA(0, 1), a2 + hstep, voffA);
;             PG8_WAIT_V(8); PG8_WAIT_L(0); PG8_BAR; PG8_MMA(0, 0, At, B0); PG8_MMA(0, 1, At, B1); PG8_BAR; PG8_SCHED;
;             PG8_LDA(At, 1, 1); PG8_STAGE(PG8_SB(1, 0), b3, voffB); PG8_STAGE(PG8_SB(1, 1), b3 + hstep, voffB); PG8_STAGE(PG8_SA(1, 0), a3, voffA);
;             PG8_WAIT_V(8); PG8_WAIT_L(0); PG8_BAR; PG8_MMA(1, 0, At, B0); PG8_MMA(1, 1, At, B1); PG8_BAR; PG8_SCHED;
;     ...
;         if constexpr (ALIGN_EPI) { if (wr == 0) PG8_BAR; }
	s_add_i32 s54, 0, 0x18000
	s_add_i32 s55, 0, 0x1c000
	v_add_u32_e32 v142, s54, v199
	v_add_u32_e32 v182, s55, v199
	ds_read_b128 v[122:125], v142
	ds_read_b128 v[134:137], v142 offset:1024
	ds_read_b128 v[138:141], v142 offset:2048
	ds_read_b128 v[142:145], v142 offset:3072
	ds_read_b128 v[146:149], v182
	ds_read_b128 v[150:153], v182 offset:1024
	ds_read_b128 v[154:157], v182 offset:2048
	ds_read_b128 v[182:185], v182 offset:3072
	s_add_u32 s22, s28, 0x160000
	s_addc_u32 s23, s29, 0
	s_mov_b32 m0, s48
	ds_read_b128 v[186:189], v202 offset:32768
	ds_read_b128 v[190:193], v202 offset:33792
	ds_read_b128 v[194:197], v202 offset:34816
	ds_read_b128 v[218:221], v202 offset:35840
	ds_read_b128 v[222:225], v202 offset:36864
	ds_read_b128 v[226:229], v202 offset:37888
	ds_read_b128 v[230:233], v202 offset:38912
	ds_read_b128 v[234:237], v202 offset:39936
	global_load_lds_dwordx4 v162, s[22:23]
	s_mov_b32 m0, s49
	s_nop 0
	global_load_lds_dwordx4 v160, s[22:23]
	s_waitcnt vmcnt(8)
	s_waitcnt lgkmcnt(0)
	s_barrier
	v_mfma_f32_16x16x32_bf16 v[130:133], v[122:125], v[186:189], v[130:133]
	v_mfma_f32_16x16x32_bf16 v[126:129], v[138:141], v[186:189], v[126:129]
	v_mfma_f32_16x16x32_bf16 v[110:113], v[122:125], v[194:197], v[110:113]
	v_mfma_f32_16x16x32_bf16 v[106:109], v[138:141], v[194:197], v[106:109]
	v_mfma_f32_16x16x32_bf16 v[94:97], v[122:125], v[222:225], v[94:97]
	v_mfma_f32_16x16x32_bf16 v[90:93], v[138:141], v[222:225], v[90:93]
	v_mfma_f32_16x16x32_bf16 v[78:81], v[122:125], v[230:233], v[78:81]
	v_mfma_f32_16x16x32_bf16 v[74:77], v[138:141], v[230:233], v[74:77]
	v_mfma_f32_16x16x32_bf16 v[130:133], v[134:137], v[190:193], v[130:133]
	v_mfma_f32_16x16x32_bf16 v[126:129], v[142:145], v[190:193], v[126:129]
	v_mfma_f32_16x16x32_bf16 v[110:113], v[134:137], v[218:221], v[110:113]
	v_mfma_f32_16x16x32_bf16 v[106:109], v[142:145], v[218:221], v[106:109]
	v_mfma_f32_16x16x32_bf16 v[94:97], v[134:137], v[226:229], v[94:97]
	v_mfma_f32_16x16x32_bf16 v[90:93], v[142:145], v[226:229], v[90:93]
	v_mfma_f32_16x16x32_bf16 v[78:81], v[134:137], v[234:237], v[78:81]
	v_mfma_f32_16x16x32_bf16 v[74:77], v[142:145], v[234:237], v[74:77]
	v_mfma_f32_16x16x32_bf16 v[118:121], v[146:149], v[186:189], v[118:121]
	v_mfma_f32_16x16x32_bf16 v[114:117], v[154:157], v[186:189], v[114:117]
	v_mfma_f32_16x16x32_bf16 v[102:105], v[146:149], v[194:197], v[102:105]
	v_mfma_f32_16x16x32_bf16 v[98:101], v[154:157], v[194:197], v[98:101]
	v_mfma_f32_16x16x32_bf16 v[86:89], v[146:149], v[222:225], v[86:89]
	v_mfma_f32_16x16x32_bf16 v[82:85], v[154:157], v[222:225], v[82:85]
	v_mfma_f32_16x16x32_bf16 v[70:73], v[146:149], v[230:233], v[70:73]
	v_mfma_f32_16x16x32_bf16 v[66:69], v[154:157], v[230:233], v[66:69]
	v_mfma_f32_16x16x32_bf16 v[118:121], v[150:153], v[190:193], v[118:121]
	v_mfma_f32_16x16x32_bf16 v[114:117], v[182:185], v[190:193], v[114:117]
	v_mfma_f32_16x16x32_bf16 v[102:105], v[150:153], v[218:221], v[102:105]
	v_mfma_f32_16x16x32_bf16 v[98:101], v[182:185], v[218:221], v[98:101]
	v_mfma_f32_16x16x32_bf16 v[86:89], v[150:153], v[226:229], v[86:89]
	v_mfma_f32_16x16x32_bf16 v[82:85], v[182:185], v[226:229], v[82:85]
	v_mfma_f32_16x16x32_bf16 v[70:73], v[150:153], v[234:237], v[70:73]
	v_mfma_f32_16x16x32_bf16 v[66:69], v[182:185], v[234:237], v[66:69]
	s_barrier
	s_add_i32 s22, s54, s2
	s_add_i32 m0, s22, 0xffffff80
	ds_read_b128 v[186:189], v202 offset:49152
	ds_read_b128 v[190:193], v202 offset:50176
	ds_read_b128 v[194:197], v202 offset:51200
	ds_read_b128 v[218:221], v202 offset:52224
	ds_read_b128 v[222:225], v202 offset:53248
	ds_read_b128 v[226:229], v202 offset:54272
	ds_read_b128 v[230:233], v202 offset:55296
	ds_read_b128 v[234:237], v202 offset:56320
	global_load_lds_dwordx4 v0, s[26:27] offset:128
	s_add_i32 m0, s22, 0x2000
	s_add_u32 s22, s26, 0x160080
	v_lshl_add_u64 v[238:239], v[240:241], 0, s[34:35]
	s_addc_u32 s23, s27, 0
	s_add_i32 s26, s55, s2
	global_load_lds_dwordx4 v[238:239], off
	s_mov_b32 m0, s26
	s_nop 0
	global_load_lds_dwordx4 v0, s[22:23]
	s_add_i32 m0, s26, 0x2000
	s_nop 0
	global_load_lds_dwordx4 v158, s[22:23]
	s_add_i32 m0, s51, 0xffffff80
	s_nop 0
	global_load_lds_dwordx4 v162, s[28:29] offset:128
	s_add_i32 m0, s52, 0xffffff80
	s_nop 0
	global_load_lds_dwordx4 v160, s[28:29] offset:128
	s_waitcnt vmcnt(8)
	s_waitcnt lgkmcnt(0)
	s_barrier
	v_mfma_f32_16x16x32_bf16 v[62:65], v[122:125], v[186:189], v[62:65]
	v_mfma_f32_16x16x32_bf16 v[58:61], v[138:141], v[186:189], v[58:61]
	v_mfma_f32_16x16x32_bf16 v[46:49], v[122:125], v[194:197], v[46:49]
	v_mfma_f32_16x16x32_bf16 v[42:45], v[138:141], v[194:197], v[42:45]
	v_mfma_f32_16x16x32_bf16 v[30:33], v[122:125], v[222:225], v[30:33]
	v_mfma_f32_16x16x32_bf16 v[26:29], v[138:141], v[222:225], v[26:29]
	v_mfma_f32_16x16x32_bf16 v[14:17], v[122:125], v[230:233], v[14:17]
	v_mfma_f32_16x16x32_bf16 v[10:13], v[138:141], v[230:233], v[10:13]
	v_mfma_f32_16x16x32_bf16 v[62:65], v[134:137], v[190:193], v[62:65]
	v_mfma_f32_16x16x32_bf16 v[58:61], v[142:145], v[190:193], v[58:61]
	v_mfma_f32_16x16x32_bf16 v[46:49], v[134:137], v[218:221], v[46:49]
	v_mfma_f32_16x16x32_bf16 v[42:45], v[142:145], v[218:221], v[42:45]
	v_mfma_f32_16x16x32_bf16 v[30:33], v[134:137], v[226:229], v[30:33]
	v_mfma_f32_16x16x32_bf16 v[26:29], v[142:145], v[226:229], v[26:29]
	v_mfma_f32_16x16x32_bf16 v[14:17], v[134:137], v[234:237], v[14:17]
	v_mfma_f32_16x16x32_bf16 v[10:13], v[142:145], v[234:237], v[10:13]
	v_mfma_f32_16x16x32_bf16 v[54:57], v[146:149], v[186:189], v[54:57]
	v_mfma_f32_16x16x32_bf16 v[50:53], v[154:157], v[186:189], v[50:53]
	v_mfma_f32_16x16x32_bf16 v[38:41], v[146:149], v[194:197], v[38:41]
	v_mfma_f32_16x16x32_bf16 v[34:37], v[154:157], v[194:197], v[34:37]
	v_mfma_f32_16x16x32_bf16 v[22:25], v[146:149], v[222:225], v[22:25]
	v_mfma_f32_16x16x32_bf16 v[18:21], v[154:157], v[222:225], v[18:21]
	v_mfma_f32_16x16x32_bf16 v[6:9], v[146:149], v[230:233], v[6:9]
	v_mfma_f32_16x16x32_bf16 v[2:5], v[154:157], v[230:233], v[2:5]
	v_mfma_f32_16x16x32_bf16 v[54:57], v[150:153], v[190:193], v[54:57]
	v_mfma_f32_16x16x32_bf16 v[50:53], v[182:185], v[190:193], v[50:53]
	v_mfma_f32_16x16x32_bf16 v[38:41], v[150:153], v[218:221], v[38:41]
	v_mfma_f32_16x16x32_bf16 v[34:37], v[182:185], v[218:221], v[34:37]
	v_mfma_f32_16x16x32_bf16 v[22:25], v[150:153], v[226:229], v[22:25]
	v_mfma_f32_16x16x32_bf16 v[18:21], v[182:185], v[226:229], v[18:21]
	v_mfma_f32_16x16x32_bf16 v[6:9], v[150:153], v[234:237], v[6:9]
	v_mfma_f32_16x16x32_bf16 v[2:5], v[182:185], v[234:237], v[2:5]
	s_barrier
	s_add_i32 s78, s78, 2
	s_add_u32 s44, s44, 0x100
	s_addc_u32 s45, s45, 0
	s_cmpk_gt_u32 s78, 0x55
	s_mov_b64 s[22:23], s[24:25]
	s_cbranch_scc0 .LBB0_802
	s_and_b64 vcc, exec, s[6:7]
	s_cbranch_vccz .LBB0_805
	s_barrier
